# attention: V image identity key order (drop 8 permlane32_swap per tile), LDS reads issued before K/V LDS-DMA pieces
# speedup vs baseline: 1.0043x; 1.0043x over previous
; #define CUR_TID() (wave_s * 64 + LANE_ID())
; template <int mode> ...
;     ...
;   const int wid = __builtin_amdgcn_readfirstlane(tid >> 6), lane = tid & 63, r32 = lane & 31, hi = lane >> 5;
;   const unsigned lds0 = (unsigned)(uintptr_t)lds;
;   float* ws = (float*)(lds + A_LDS_WS) + wid * 64; float* li_l = ws; float* al_l = ws + 32;
;   unsigned koff[2], voff[4];
; #pragma unroll
;   for (int i = 0; i < 2; ++i) { const int row = (wid * 2 + i) * 4 + (lane >> 4), chunk = (lane & 15) ^ (((row & 7) << 1) | ((row >> 3) & 1)); koff[i] = (unsigned)(row * (LDP * 2) + chunk * 16); }
; #pragma unroll
;   for (int i = 0; i < 4; ++i) { const int q = (wid & 3) * 4 + i, subtile = q * 2 + (lane >> 5), kk = (subtile >> 2) * 8 + ((lane & 31) >> 2);
;     const int k = (kk & ~0xC) | ((kk & 4) << 1) | ((kk & 8) >> 1), col = (subtile & 3) * 32 + (lane & 3) * 8;
;     voff[i] = (unsigned)(k * (LDP * 2) + ((wid >> 2) * 128 + col) * 2); }
;   const char* Kb = (const char*)Kh; const char* Vb = (const char*)Vh;
;   const unsigned kdst = lds0 + A_LDS_K + wid * 2048, vdst = lds0 + A_LDS_V + (wid >> 2) * 16384 + (wid & 3) * 4096;
;     ...
;   bf16x8 qr[8];
;   { const hbf* Qw = Qb + (long)(wid * QBLK + r32) * LDQ + hi * 8;
; #pragma unroll
;     for (int d0 = 0; d0 < 8; ++d0) qr[d0] = *reinterpret_cast<const bf16x8*>(Qw + d0 * 16); }
; __global__ void __launch_bounds__(NWAVES * 64, 2) mega_fwd(Args args) {
;     ...
;                 if (G == 256) { const int xcd = bx & 7, jb = bx >> 3;
;                     if (g == 0) { set = (xcd >> 1) + 4 * i; qb = (xcd & 1) * 32 + jb; } else { set = xcd * 2 + (jb >> 4) + 16 * i; qb = jb & 15; } }
;                 else { const int u = bx + i * G; if (g == 0) { set = u >> 6; qb = u & 63; } else { set = u >> 4; qb = u & 15; } }
;                 const int h = set & 7, sq = set >> 3;
;                 const size_t krow = (size_t)sq * SEQ, qrow = krow + (size_t)qb * 256;
;                 const att::hbf* Vp = (const att::hbf*)(PROJ + krow * LDP + C_DV + h * 256);
;                 float* stash = OS + (size_t)bx * 65536;
;                 { const att::hbf* Qp = (const att::hbf*)(PROJ + qrow * LDP + C_DQ + (2 * h) * 128);
;                   const att::hbf* Kp = (const att::hbf*)(PROJ + krow * LDP + C_DK + (2 * h) * 128);
;                   att::attn256_unit<0>(Qp, Kp, Vp, SEQ, (char*)lds, CUR_TID(), stash, nullptr, 0.f, nullptr); }
.LBB0_345:
	s_ashr_i32 s4, s10, 3
	s_ashr_i32 s5, s4, 31
	s_ashr_i32 s25, s24, 31
	s_lshl_b64 s[4:5], s[4:5], s72
	s_lshl_b64 s[6:7], s[24:25], 8
	s_add_u32 s46, s4, s6
	s_addc_u32 s47, s5, s7
	s_mul_i32 s0, s5, 0x6000
	s_mul_hi_u32 s5, s4, 0x6000
	s_add_i32 s11, s5, s0
	s_mul_i32 s38, s4, 0x6000
	s_add_u32 s0, s82, s38
	s_addc_u32 s6, s83, s11
	s_lshl_b32 s4, s10, 8
	s_and_b32 s4, s4, 0x700
	s_lshl_b32 s4, s4, 1
	s_add_u32 s9, s0, s4
	s_addc_u32 s12, s6, 0
	s_add_u32 s94, s9, 0x5000
	s_mul_i32 s5, s47, 0x6000
	s_mul_hi_u32 s7, s46, 0x6000
	s_addc_u32 s95, s12, 0
	s_add_i32 s7, s7, s5
	s_mul_i32 s5, s46, 0x6000
	s_add_u32 s5, s82, s5
	s_addc_u32 s7, s83, s7
	s_add_u32 s50, s5, 0x3000
	s_addc_u32 s51, s7, 0
	s_add_u32 s40, s50, s4
	s_addc_u32 s41, s51, 0
	s_add_u32 s5, s0, 0x4000
	s_addc_u32 s6, s6, 0
	v_mbcnt_lo_u32_b32 v0, -1, 0
	v_mbcnt_hi_u32_b32 v0, -1, v0
	s_add_u32 s24, s5, s4
	v_add_u32_e32 v1, s59, v0
	s_addc_u32 s25, s6, 0
	v_readfirstlane_b32 s8, v1
	s_ashr_i32 s28, s8, 6
	v_and_b32_e32 v0, 31, v1
	v_bfe_u32 v2, v1, 5, 1
	v_lshl_or_b32 v3, s28, 5, v0
	v_mov_b64_e32 v[4:5], s[40:41]
	v_mad_i64_i32 v[4:5], s[40:41], v3, s68, v[4:5]
	v_lshlrev_b32_e32 v198, 4, v2
	v_mov_b32_e32 v199, v193
	v_lshl_add_u64 v[4:5], v[4:5], 0, v[198:199]
	global_load_dwordx4 v[160:163], v[4:5], off offset:224
	global_load_dwordx4 v[164:167], v[4:5], off offset:192
	global_load_dwordx4 v[168:171], v[4:5], off offset:160
	global_load_dwordx4 v[172:175], v[4:5], off offset:128
	global_load_dwordx4 v[176:179], v[4:5], off offset:96
	global_load_dwordx4 v[180:183], v[4:5], off offset:64
	global_load_dwordx4 v[184:187], v[4:5], off offset:32
	global_load_dwordx4 v[188:191], v[4:5], off
	v_bfe_u32 v3, v1, 4, 2
	v_lshlrev_b32_e32 v7, 4, v1
	v_bfe_u32 v5, v1, 2, 3
	v_lshrrev_b32_e32 v6, 1, v1
	v_or_b32_e32 v9, 4, v3
	v_and_b32_e32 v7, 48, v7
	v_lshlrev_b32_e32 v10, 6, v2
	s_and_b32 s0, s8, 0xffffff00
	s_lshl_b32 s7, s8, 6
	s_lshl_b32 s13, s28, 3
	s_lshl_b32 s39, s28, 12
	v_and_b32_e32 v4, 15, v1
	v_lshlrev_b32_e32 v8, 1, v3
	v_and_b32_e32 v6, 8, v6
	v_lshlrev_b32_e32 v11, 1, v9
	s_and_b32 s29, s28, 1
	v_lshl_or_b32 v5, s28, 4, v5
	v_or3_b32 v7, s0, v7, v10
	s_lshl_b32 s0, s28, 11
	s_and_b32 s7, s7, 0xffffc000
	v_or_b32_e32 v3, s13, v3
	v_or_b32_e32 v9, s13, v9
	s_and_b32 s13, s39, 0x3000
	v_bitop3_b32 v8, v8, v4, s29 bitop3:0x36
	v_and_b32_e32 v5, 55, v5
	v_or_b32_e32 v6, 0x80, v7
	v_mul_lo_u32 v3, v3, s68
	v_mov_b32_e32 v10, 0x30000
	s_cmp_lg_u32 0, -1
	v_bitop3_b32 v4, v11, v4, s29 bitop3:0x36
	v_mul_lo_u32 v9, v9, s68
	v_mad_u32_u24 v204, v5, s68, v7
	v_mad_u32_u24 v206, v5, s68, v6
	v_mad_u32_u24 v5, v5, s68, v10
	v_lshl_or_b32 v192, v8, 4, v3
	s_cselect_b32 s29, 0, 0
	v_mov_b32_e32 v203, v193
	v_lshl_add_u32 v202, v4, 4, v9
	v_add_u32_e32 v208, v5, v7
	v_add_u32_e32 v210, v5, v6
	s_add_i32 s0, s0, s29
	s_add_i32 s7, s29, s7
	v_lshl_add_u64 v[6:7], s[24:25], 0, v[192:193]
	v_mov_b32_e32 v205, v193
	v_lshl_add_u64 v[8:9], s[24:25], 0, v[202:203]
	s_add_i32 s7, s7, s13
	s_add_i32 s13, s0, 0x400
	v_lshl_add_u64 v[4:5], s[94:95], 0, v[204:205]
	s_add_i32 s7, s7, 0xc000
	v_mov_b32_e32 v207, v193
	v_mov_b32_e32 v209, v193
	v_mov_b32_e32 v211, v193
	s_waitcnt vmcnt(0)
	s_mov_b32 s29, m0
	s_mov_b32 m0, s0
	s_nop 0
	global_load_lds_dwordx4 v[6:7], off
	s_mov_b32 m0, s29
	s_nop 0
	s_mov_b32 s29, m0
	s_mov_b32 m0, s13
	s_nop 0
	global_load_lds_dwordx4 v[8:9], off
	s_mov_b32 m0, s29
	s_mov_b32 s13, m0
	s_mov_b32 m0, s7
	s_nop 0
	global_load_lds_dwordx4 v[4:5], off
	s_mov_b32 m0, s13
	s_add_i32 s13, s7, 0x400
	v_lshl_add_u64 v[4:5], s[94:95], 0, v[206:207]
	s_mov_b32 s29, m0
	s_mov_b32 m0, s13
	s_nop 0
	global_load_lds_dwordx4 v[4:5], off
	s_mov_b32 m0, s29
	s_add_i32 s13, s7, 0x800
	v_lshl_add_u64 v[4:5], s[94:95], 0, v[208:209]
	s_mov_b32 s29, m0
	s_mov_b32 m0, s13
	s_nop 0
	global_load_lds_dwordx4 v[4:5], off
	s_mov_b32 m0, s29
	s_add_i32 s13, s7, 0xc00
	s_add_u32 s24, s24, 0x180000
	v_lshl_add_u64 v[4:5], s[94:95], 0, v[210:211]
	s_mov_b32 s29, m0
	s_mov_b32 m0, s13
	s_nop 0
	global_load_lds_dwordx4 v[4:5], off
	s_mov_b32 m0, s29
	s_addc_u32 s25, s25, 0
	s_add_i32 s13, s0, 0x4000
	v_lshl_add_u64 v[4:5], s[24:25], 0, v[192:193]
	s_mov_b32 s29, m0
	s_mov_b32 m0, s13
	s_nop 0
	global_load_lds_dwordx4 v[4:5], off
	s_mov_b32 m0, s29
	s_add_i32 s13, s0, 0x4400
	s_add_u32 s52, s9, 0x185000
	v_lshl_add_u64 v[4:5], s[24:25], 0, v[202:203]
	s_mov_b32 s24, m0
	s_mov_b32 m0, s13
	s_nop 0
	global_load_lds_dwordx4 v[4:5], off
	s_mov_b32 m0, s24
	s_addc_u32 s53, s12, 0
	s_add_i32 s9, s7, 0x8000
	v_lshl_add_u64 v[4:5], s[52:53], 0, v[204:205]
	s_mov_b32 s12, m0
	s_mov_b32 m0, s9
	s_nop 0
	global_load_lds_dwordx4 v[4:5], off
	s_mov_b32 m0, s12
	v_lshl_add_u64 v[4:5], s[52:53], 0, v[206:207]
	s_add_i32 s9, s7, 0x8400
	s_mov_b32 s12, m0
	s_mov_b32 m0, s9
	s_nop 0
	global_load_lds_dwordx4 v[4:5], off
	s_mov_b32 m0, s12
	v_lshl_add_u64 v[4:5], s[52:53], 0, v[208:209]
	s_add_i32 s9, s7, 0x8800
	s_mov_b32 s12, m0
	s_mov_b32 m0, s9
	s_nop 0
	global_load_lds_dwordx4 v[4:5], off
	s_mov_b32 m0, s12
	v_lshl_add_u64 v[4:5], s[52:53], 0, v[210:211]
	s_add_i32 s9, s7, 0x8c00
	s_mov_b32 s12, m0
	s_mov_b32 m0, s9
	s_nop 0
	global_load_lds_dwordx4 v[4:5], off
	s_mov_b32 m0, s12
	s_waitcnt vmcnt(6) lgkmcnt(0)
	s_barrier
	s_cmp_lt_i32 s28, 4
	s_cbranch_scc1 .LBB0_347
	s_barrier

; #define SBAR() __builtin_amdgcn_sched_barrier(0)
; #define KRD(A, B, d0) do { const int ad_ = (kc ^ ((d0) << 5)) + kbt; A = lds_rd128<0>(ad_); B = lds_rd128<8192>(ad_); } while (0)
; #define KW(N) do { asm volatile("s_waitcnt lgkmcnt(" #N ")" ::: "memory"); SBAR(); } while (0)
; #define DMA_K(t, sl) do { const char* b_ = Kb + (size_t)(t) * TSTRIDE; const unsigned d_ = RFL(kdst + (sl) * 16384); glds16(b_ + koff[0], d_); glds16(b_ + koff[1], d_ + 1024); } while (0)
; __device__ __forceinline__ void qkt_pipe(f32x16& p0, f32x16& p1, int kbt, int kc, const bf16x8* qr, const f32x16& z) {
;   bf16x8 a0, b0, a1, b1, a2, b2, a3, b3;
;     ...
;   KRD(a0, b0, 0); KRD(a1, b1, 1); KRD(a2, b2, 2); KRD(a3, b3, 3);
;   KW(6); p0 = __builtin_amdgcn_mfma_f32_32x32x16_bf16(a0, qr[0], z, 0, 0, 0);  p1 = __builtin_amdgcn_mfma_f32_32x32x16_bf16(b0, qr[0], z, 0, 0, 0);  SBAR(); KRD(a0, b0, 4);
;   KW(6); p0 = __builtin_amdgcn_mfma_f32_32x32x16_bf16(a1, qr[1], p0, 0, 0, 0); p1 = __builtin_amdgcn_mfma_f32_32x32x16_bf16(b1, qr[1], p1, 0, 0, 0); SBAR(); KRD(a1, b1, 5);
;   KW(6); p0 = __builtin_amdgcn_mfma_f32_32x32x16_bf16(a2, qr[2], p0, 0, 0, 0); p1 = __builtin_amdgcn_mfma_f32_32x32x16_bf16(b2, qr[2], p1, 0, 0, 0); SBAR(); KRD(a2, b2, 6);
;   KW(6); p0 = __builtin_amdgcn_mfma_f32_32x32x16_bf16(a3, qr[3], p0, 0, 0, 0); p1 = __builtin_amdgcn_mfma_f32_32x32x16_bf16(b3, qr[3], p1, 0, 0, 0); SBAR(); KRD(a3, b3, 7);
;   KW(6); p0 = __builtin_amdgcn_mfma_f32_32x32x16_bf16(a0, qr[4], p0, 0, 0, 0); p1 = __builtin_amdgcn_mfma_f32_32x32x16_bf16(b0, qr[4], p1, 0, 0, 0); SBAR();
;   KW(4); p0 = __builtin_amdgcn_mfma_f32_32x32x16_bf16(a1, qr[5], p0, 0, 0, 0); p1 = __builtin_amdgcn_mfma_f32_32x32x16_bf16(b1, qr[5], p1, 0, 0, 0); SBAR();
;   KW(2); p0 = __builtin_amdgcn_mfma_f32_32x32x16_bf16(a2, qr[6], p0, 0, 0, 0); p1 = __builtin_amdgcn_mfma_f32_32x32x16_bf16(b2, qr[6], p1, 0, 0, 0); SBAR();
;   KW(0); p0 = __builtin_amdgcn_mfma_f32_32x32x16_bf16(a3, qr[7], p0, 0, 0, 0); p1 = __builtin_amdgcn_mfma_f32_32x32x16_bf16(b3, qr[7], p1, 0, 0, 0);
; template <int mode> ...
;     ...
;   for (int j = 0; j < NT; ++j) {
;     const bool more = j + 2 < NT;
;     if (more) DMA_K(j + 2, s2);
;     f32x16 p0, p1; bf16x8 pa0, pa1, pa2, pa3;
;     __builtin_amdgcn_s_setprio(2);
;     { f32x16 negm;
; #pragma unroll
;       for (int r = 0; r < 16; ++r) negm[r] = -m_reg;
;       qkt_pipe(p0, p1, kb0 + s0 * 16384, kc, qr, negm); }
.LBB0_348:
	s_add_i32 s12, s10, 2
	s_cmp_lt_u32 s12, s74
	s_cselect_b64 s[56:57], -1, 0
	s_cmp_ge_u32 s12, s74
	s_cselect_b64 s[90:91], -1, 0
	s_mov_b32 s11, s24
	s_and_b64 vcc, exec, s[90:91]
	s_setprio 2
	v_lshl_add_u32 v212, s11, 14, v199
	v_add_u32_e32 v144, v212, v213
	ds_read_b128 v[194:197], v144 offset:0
	ds_read_b128 v[226:229], v144 offset:0x2000
	v_xor_b32_e32 v144, 32, v213
	v_add_u32_e32 v144, v212, v144
	ds_read_b128 v[230:233], v144 offset:0
	ds_read_b128 v[234:237], v144 offset:0x2000
	v_xor_b32_e32 v144, 64, v213
	v_add_u32_e32 v144, v212, v144
	ds_read_b128 v[238:241], v144 offset:0
	ds_read_b128 v[242:245], v144 offset:0x2000
	v_xor_b32_e32 v144, 0x60, v213
	v_add_u32_e32 v144, v212, v144
	ds_read_b128 v[246:249], v144 offset:0
	ds_read_b128 v[214:217], v144 offset:0x2000
	s_cbranch_vccnz .Lq0_nodma
	s_add_u32 s24, s38, 0xfffff000
	s_addc_u32 s25, s39, -1
	s_lshl_b32 s12, s9, 14
	s_add_i32 s12, s12, s0
	v_lshl_add_u64 v[128:129], s[24:25], 0, v[192:193]
	s_mov_b32 s13, m0
	s_mov_b32 m0, s12
	s_nop 0
	global_load_lds_dwordx4 v[128:129], off
	s_mov_b32 m0, s13
	v_lshl_add_u64 v[128:129], s[24:25], 0, v[202:203]
	s_addk_i32 s12, 0x400
	s_mov_b32 s13, m0
	s_mov_b32 m0, s12
	s_nop 0
	global_load_lds_dwordx4 v[128:129], off
	s_mov_b32 m0, s13
.Lq0_nodma:
	s_waitcnt lgkmcnt(6)
	v_xor_b32_e32 v128, 0x80000000, v224
	v_mov_b32_e32 v129, v128
	v_mov_b32_e32 v130, v128
	v_mov_b32_e32 v131, v128
	v_mov_b32_e32 v132, v128
	v_mov_b32_e32 v133, v128
	v_mov_b32_e32 v134, v128
	v_mov_b32_e32 v135, v128
	v_mov_b32_e32 v136, v128
	v_mov_b32_e32 v137, v128
	v_mov_b32_e32 v138, v128
	v_mov_b32_e32 v139, v128
	v_mov_b32_e32 v140, v128
	v_mov_b32_e32 v141, v128
	v_mov_b32_e32 v142, v128
	v_mov_b32_e32 v143, v128
	s_nop 1
	v_mfma_f32_32x32x16_bf16 v[144:159], v[194:197], v[188:191], v[128:143]
	v_mfma_f32_32x32x16_bf16 v[128:143], v[226:229], v[188:191], v[128:143]
	v_xor_b32_e32 v194, 0x80, v213
	v_add_u32_e32 v220, v212, v194
	ds_read_b128 v[194:197], v220 offset:0
	ds_read_b128 v[226:229], v220 offset:0x2000
	s_waitcnt lgkmcnt(6)
	v_mfma_f32_32x32x16_bf16 v[144:159], v[230:233], v[184:187], v[144:159]
	v_mfma_f32_32x32x16_bf16 v[128:143], v[234:237], v[184:187], v[128:143]
	v_xor_b32_e32 v220, 0xa0, v213
	v_add_u32_e32 v220, v212, v220
	ds_read_b128 v[230:233], v220 offset:0
	ds_read_b128 v[234:237], v220 offset:0x2000
	s_waitcnt lgkmcnt(6)
	v_mfma_f32_32x32x16_bf16 v[144:159], v[238:241], v[180:183], v[144:159]
	v_mfma_f32_32x32x16_bf16 v[128:143], v[242:245], v[180:183], v[128:143]
	v_xor_b32_e32 v220, 0xc0, v213
	v_add_u32_e32 v220, v212, v220
	ds_read_b128 v[238:241], v220 offset:0
	ds_read_b128 v[242:245], v220 offset:0x2000
	s_waitcnt lgkmcnt(6)
	v_mfma_f32_32x32x16_bf16 v[144:159], v[246:249], v[176:179], v[144:159]
	v_mfma_f32_32x32x16_bf16 v[128:143], v[214:217], v[176:179], v[128:143]
	v_xor_b32_e32 v214, 0xe0, v213
	v_add_u32_e32 v212, v212, v214
	ds_read_b128 v[214:217], v212 offset:0
	ds_read_b128 v[246:249], v212 offset:0x2000
	s_waitcnt lgkmcnt(6)
	v_mfma_f32_32x32x16_bf16 v[144:159], v[194:197], v[172:175], v[144:159]
	v_mfma_f32_32x32x16_bf16 v[128:143], v[226:229], v[172:175], v[128:143]
	s_waitcnt lgkmcnt(4)
	v_mfma_f32_32x32x16_bf16 v[144:159], v[230:233], v[168:171], v[144:159]
	v_mfma_f32_32x32x16_bf16 v[128:143], v[234:237], v[168:171], v[128:143]
	s_waitcnt lgkmcnt(2)
	v_mfma_f32_32x32x16_bf16 v[144:159], v[238:241], v[164:167], v[144:159]
	v_mfma_f32_32x32x16_bf16 v[128:143], v[242:245], v[164:167], v[128:143]
	s_waitcnt lgkmcnt(0)
	v_mfma_f32_32x32x16_bf16 v[144:159], v[214:217], v[160:163], v[144:159]
	s_cmp_eq_u32 s10, 0
	s_cselect_b64 s[62:63], -1, 0
	s_cmp_lg_u32 s10, 0
	v_mfma_f32_32x32x16_bf16 v[128:143], v[246:249], v[160:163], v[128:143]
	s_nop 7
	v_max_f32_e32 v194, v145, v145
	v_max_f32_e32 v195, v144, v144
	v_max_f32_e32 v194, v195, v194
	v_max3_f32 v194, v194, v146, v147
	v_max3_f32 v194, v194, v148, v149
	v_max3_f32 v194, v194, v150, v151
	v_max3_f32 v194, v194, v152, v153
	v_max3_f32 v194, v194, v154, v155
	v_max3_f32 v194, v194, v156, v157
	v_max3_f32 v194, v194, v158, v159
	v_max3_f32 v194, v194, v128, v129
	v_max3_f32 v194, v194, v130, v131
	v_max3_f32 v194, v194, v132, v133
	v_max3_f32 v194, v194, v134, v135
	v_max3_f32 v194, v194, v136, v137
	v_max3_f32 v194, v194, v138, v139
	v_max3_f32 v194, v194, v140, v141
	v_max3_f32 v194, v194, v142, v143
	v_mov_b32_e32 v195, v194
	s_nop 1
	v_permlane32_swap_b32_e32 v194, v195
	v_max_f32_e32 v195, v195, v195
	v_max_f32_e32 v194, v194, v194
	v_max_f32_e32 v226, v194, v195
	s_cbranch_scc0 .LBB0_371
	v_cmp_lt_f32_e32 vcc, s30, v226
	s_mov_b64 s[24:25], 0
	s_mov_b64 s[96:97], 0
	s_cbranch_vccnz .LBB0_372
	s_and_b64 vcc, exec, s[24:25]
	s_cbranch_vccnz .LBB0_373

; __device__ __forceinline__ float softmax_rel(f32x16& p0, f32x16& p1, bool first, float& m_reg, float& l_reg, bf16x8& pa0, bf16x8& pa1, bf16x8& pa2, bf16x8& pa3) {
;     ...
; #pragma unroll
;   for (int r = 0; r < 16; ++r) p0[r] = __builtin_amdgcn_exp2f(p0[r]);
; #pragma unroll
;   for (int r = 0; r < 16; ++r) p1[r] = __builtin_amdgcn_exp2f(p1[r]);
;   float ps = 0;
; #pragma unroll
;   for (int r = 0; r < 16; ++r) ps += p0[r];
; #pragma unroll
;   for (int r = 0; r < 16; ++r) ps += p1[r];
;   { auto rr = __builtin_amdgcn_permlane32_swap(__float_as_uint(ps), __float_as_uint(ps), false, false);
;     ps = __uint_as_float(rr[0]) + __uint_as_float(rr[1]); }
;   l_reg = l_reg * alpha + ps;
;   PK4(p0, 0, pa0); PK4(p0, 8, pa1); PK4(p1, 0, pa2); PK4(p1, 8, pa3);
;   return alpha;
.LBB0_355:
	v_exp_f32_e32 v144, v144
	v_exp_f32_e32 v145, v145
	v_exp_f32_e32 v146, v146
	v_exp_f32_e32 v147, v147
	v_exp_f32_e32 v148, v148
	v_exp_f32_e32 v194, v128
	v_add_f32_e32 v128, 0, v144
	v_exp_f32_e32 v149, v149
	v_add_f32_e32 v128, v145, v128
	v_exp_f32_e32 v150, v150
	v_add_f32_e32 v128, v146, v128
	v_exp_f32_e32 v151, v151
	v_add_f32_e32 v128, v147, v128
	v_exp_f32_e32 v152, v152
	v_add_f32_e32 v128, v148, v128
	v_exp_f32_e32 v153, v153
	v_add_f32_e32 v128, v149, v128
	v_exp_f32_e32 v154, v154
	v_add_f32_e32 v128, v150, v128
	v_exp_f32_e32 v155, v155
	v_add_f32_e32 v128, v151, v128
	v_exp_f32_e32 v156, v156
	v_add_f32_e32 v128, v152, v128
	v_exp_f32_e32 v157, v157
	v_add_f32_e32 v128, v153, v128
	v_exp_f32_e32 v158, v158
	v_add_f32_e32 v128, v154, v128
	v_exp_f32_e32 v159, v159
	v_add_f32_e32 v128, v155, v128
	v_add_f32_e32 v128, v156, v128
	v_exp_f32_e32 v195, v129
	v_add_f32_e32 v128, v157, v128
	v_exp_f32_e32 v196, v130
	v_add_f32_e32 v128, v158, v128
	v_exp_f32_e32 v197, v131
	v_add_f32_e32 v128, v159, v128
	v_exp_f32_e32 v214, v132
	v_add_f32_e32 v128, v194, v128
	v_exp_f32_e32 v215, v133
	v_add_f32_e32 v128, v195, v128
	v_exp_f32_e32 v216, v134
	v_add_f32_e32 v128, v196, v128
	v_exp_f32_e32 v217, v135
	v_add_f32_e32 v128, v197, v128
	v_exp_f32_e32 v220, v136
	v_add_f32_e32 v128, v214, v128
	v_exp_f32_e32 v221, v137
	v_add_f32_e32 v128, v215, v128
	v_exp_f32_e32 v222, v138
	v_add_f32_e32 v128, v216, v128
	v_exp_f32_e32 v228, v139
	v_add_f32_e32 v128, v217, v128
	v_exp_f32_e32 v229, v140
	v_add_f32_e32 v128, v220, v128
	v_exp_f32_e32 v230, v141
	v_add_f32_e32 v128, v221, v128
	v_exp_f32_e32 v231, v142
	v_add_f32_e32 v128, v222, v128
	v_exp_f32_e32 v143, v143
	v_add_f32_e32 v128, v228, v128
	v_add_f32_e32 v128, v229, v128
	v_add_f32_e32 v128, v230, v128
	v_add_f32_e32 v128, v231, v128
	v_add_f32_e32 v212, v143, v128
	v_mov_b32_e32 v227, v212
	v_cvt_pk_bf16_f32 v128, v144, v145
	v_cvt_pk_bf16_f32 v129, v146, v147
	v_cvt_pk_bf16_f32 v130, v148, v149
	v_cvt_pk_bf16_f32 v131, v150, v151
	v_cvt_pk_bf16_f32 v132, v152, v153
	v_cvt_pk_bf16_f32 v133, v154, v155
	v_cvt_pk_bf16_f32 v134, v156, v157
	v_cvt_pk_bf16_f32 v135, v158, v159
	v_cvt_pk_bf16_f32 v136, v194, v195
	v_cvt_pk_bf16_f32 v137, v196, v197
	v_cvt_pk_bf16_f32 v138, v214, v215
	v_cvt_pk_bf16_f32 v139, v216, v217
	v_cvt_pk_bf16_f32 v140, v220, v221
	v_cvt_pk_bf16_f32 v141, v222, v228
	v_cvt_pk_bf16_f32 v142, v229, v230
	v_cvt_pk_bf16_f32 v143, v231, v143
	s_nop 1
	v_permlane32_swap_b32_e32 v212, v227
	v_cmp_gt_f32_e32 vcc, 1.0, v226
	s_cbranch_vccz .LBB0_359
	s_and_saveexec_b64 s[24:25], s[40:41]
	ds_write_b32 v201, v226 offset:128
	s_or_b64 exec, exec, s[24:25]
	s_waitcnt lgkmcnt(0)
	v_add_u32_e32 v144, s8, v198
	ds_read_b128 v[156:159], v144 offset:224
	ds_read_b128 v[152:155], v144 offset:192
	ds_read_b128 v[148:151], v144 offset:160
	ds_read_b128 v[144:147], v144 offset:128
	s_waitcnt lgkmcnt(3)
	v_pk_mul_f32 v[124:125], v[124:125], v[156:157]
	s_waitcnt lgkmcnt(2)
	v_pk_mul_f32 v[120:121], v[120:121], v[152:153]
	s_waitcnt lgkmcnt(1)
	v_pk_mul_f32 v[116:117], v[116:117], v[148:149]
	v_pk_mul_f32 v[126:127], v[126:127], v[158:159]
	v_pk_mul_f32 v[122:123], v[122:123], v[154:155]
	v_pk_mul_f32 v[118:119], v[118:119], v[150:151]
	s_waitcnt lgkmcnt(0)
	v_pk_mul_f32 v[114:115], v[114:115], v[146:147]
	v_pk_mul_f32 v[112:113], v[112:113], v[144:145]
	v_pk_mul_f32 v[108:109], v[108:109], v[156:157]
	v_pk_mul_f32 v[104:105], v[104:105], v[152:153]
	v_pk_mul_f32 v[100:101], v[100:101], v[148:149]
	v_pk_mul_f32 v[110:111], v[110:111], v[158:159]
	v_pk_mul_f32 v[106:107], v[106:107], v[154:155]
	v_pk_mul_f32 v[102:103], v[102:103], v[150:151]
	v_pk_mul_f32 v[98:99], v[98:99], v[146:147]
	v_pk_mul_f32 v[96:97], v[96:97], v[144:145]
	v_pk_mul_f32 v[92:93], v[92:93], v[156:157]
	v_pk_mul_f32 v[88:89], v[88:89], v[152:153]
	v_pk_mul_f32 v[84:85], v[84:85], v[148:149]
	v_pk_mul_f32 v[94:95], v[94:95], v[158:159]
	v_pk_mul_f32 v[90:91], v[90:91], v[154:155]
	v_pk_mul_f32 v[86:87], v[86:87], v[150:151]
	v_pk_mul_f32 v[82:83], v[82:83], v[146:147]
	v_pk_mul_f32 v[80:81], v[80:81], v[144:145]
	v_pk_mul_f32 v[76:77], v[76:77], v[156:157]
	v_pk_mul_f32 v[72:73], v[72:73], v[152:153]
	v_pk_mul_f32 v[68:69], v[68:69], v[148:149]
	v_pk_mul_f32 v[78:79], v[78:79], v[158:159]
	v_pk_mul_f32 v[74:75], v[74:75], v[154:155]
	v_pk_mul_f32 v[70:71], v[70:71], v[150:151]
	v_pk_mul_f32 v[66:67], v[66:67], v[146:147]
	v_pk_mul_f32 v[64:65], v[64:65], v[144:145]
	v_pk_mul_f32 v[60:61], v[60:61], v[156:157]
	v_pk_mul_f32 v[56:57], v[56:57], v[152:153]
	v_pk_mul_f32 v[52:53], v[52:53], v[148:149]
	v_pk_mul_f32 v[62:63], v[62:63], v[158:159]
	v_pk_mul_f32 v[58:59], v[58:59], v[154:155]
	v_pk_mul_f32 v[54:55], v[54:55], v[150:151]
	v_pk_mul_f32 v[50:51], v[50:51], v[146:147]
	v_pk_mul_f32 v[48:49], v[48:49], v[144:145]
	v_pk_mul_f32 v[44:45], v[44:45], v[156:157]
	v_pk_mul_f32 v[40:41], v[40:41], v[152:153]
	v_pk_mul_f32 v[36:37], v[36:37], v[148:149]
	v_pk_mul_f32 v[46:47], v[46:47], v[158:159]
	v_pk_mul_f32 v[42:43], v[42:43], v[154:155]
	v_pk_mul_f32 v[38:39], v[38:39], v[150:151]
	v_pk_mul_f32 v[34:35], v[34:35], v[146:147]
	v_pk_mul_f32 v[32:33], v[32:33], v[144:145]
	v_pk_mul_f32 v[28:29], v[28:29], v[156:157]
	v_pk_mul_f32 v[24:25], v[24:25], v[152:153]
	v_pk_mul_f32 v[20:21], v[20:21], v[148:149]
	v_pk_mul_f32 v[30:31], v[30:31], v[158:159]
	v_pk_mul_f32 v[26:27], v[26:27], v[154:155]
	v_pk_mul_f32 v[22:23], v[22:23], v[150:151]
	v_pk_mul_f32 v[18:19], v[18:19], v[146:147]
	v_pk_mul_f32 v[16:17], v[16:17], v[144:145]
	v_pk_mul_f32 v[12:13], v[12:13], v[156:157]
	v_pk_mul_f32 v[8:9], v[8:9], v[152:153]
	v_pk_mul_f32 v[4:5], v[4:5], v[148:149]
	v_pk_mul_f32 v[14:15], v[14:15], v[158:159]
	v_pk_mul_f32 v[10:11], v[10:11], v[154:155]
	v_pk_mul_f32 v[6:7], v[6:7], v[150:151]
	v_pk_mul_f32 v[2:3], v[2:3], v[146:147]
	v_pk_mul_f32 v[0:1], v[0:1], v[144:145]
; #define SBAR() __builtin_amdgcn_sched_barrier(0)
; #define VF_WAIT(N) do { asm volatile("s_waitcnt lgkmcnt(" #N ")" ::: "memory"); SBAR(); } while (0)
; #define A_WAITBAR(N) asm volatile("s_waitcnt vmcnt(" #N ") lgkmcnt(0) ; A256BAR\n\ts_barrier" ::: "memory")
; #define DMA_V(t, sl) do { const char* b_ = Vb + (size_t)(t) * TSTRIDE; const unsigned d_ = RFL(vdst + (sl) * 32768); glds16(b_ + voff[0], d_); glds16(b_ + voff[1], d_ + 1024); glds16(b_ + voff[2], d_ + 2048); glds16(b_ + voff[3], d_ + 3072); } while (0)
; __device__ __forceinline__ void pv8(f32x16* o, int vb, bf16x8 pa0, bf16x8 pa1, bf16x8 pa2, bf16x8 pa3) {
;   VFrag fa, fb; const int vb2 = vb + 16384;
;   vf_read<0>(fa, vb);
;   vf_read<1>(fb, vb);  VF_WAIT(8); vf_mma(o[0], fa, pa0, pa1, pa2, pa3); SBAR();
;   vf_read<2>(fa, vb);  VF_WAIT(8); vf_mma(o[1], fb, pa0, pa1, pa2, pa3); SBAR();
;   vf_read<3>(fb, vb);  VF_WAIT(8); vf_mma(o[2], fa, pa0, pa1, pa2, pa3); SBAR();
;   vf_read<0>(fa, vb2); VF_WAIT(8); vf_mma(o[3], fb, pa0, pa1, pa2, pa3); SBAR();
;   vf_read<1>(fb, vb2); VF_WAIT(8); vf_mma(o[4], fa, pa0, pa1, pa2, pa3); SBAR();
;   vf_read<2>(fa, vb2); VF_WAIT(8); vf_mma(o[5], fb, pa0, pa1, pa2, pa3); SBAR();
;   vf_read<3>(fb, vb2); VF_WAIT(8); vf_mma(o[6], fa, pa0, pa1, pa2, pa3); SBAR();
;   VF_WAIT(0); vf_mma(o[7], fb, pa0, pa1, pa2, pa3);
; }
; template <int mode> ...
;     ...
;     __builtin_amdgcn_s_setprio(0);
;     if (more) A_WAITBAR(6); else A_WAITBAR(0);
;     if (more) DMA_V(j + 2, s2);
;     pv8(o, vb0 + s0 * 32768, pa0, pa1, pa2, pa3);
;     if (more) A_WAITBAR(6); else A_WAITBAR(0);
.LBB0_359:
	s_setprio 0
	s_and_b64 vcc, exec, s[90:91]
	s_cbranch_vccnz .Lp0_bar0
	s_waitcnt vmcnt(6) lgkmcnt(0)
	s_barrier
.LBB0_363:
	v_lshl_add_u32 v220, s11, 15, v223
	ds_read_b64_tr_b16 v[144:145], v220 offset:0
	ds_read_b64_tr_b16 v[146:147], v220 offset:0x800
	ds_read_b64_tr_b16 v[148:149], v220 offset:0x1000
	ds_read_b64_tr_b16 v[150:151], v220 offset:0x1800
	ds_read_b64_tr_b16 v[152:153], v220 offset:0x2000
	ds_read_b64_tr_b16 v[154:155], v220 offset:0x2800
	ds_read_b64_tr_b16 v[156:157], v220 offset:0x3000
	ds_read_b64_tr_b16 v[158:159], v220 offset:0x3800
	ds_read_b64_tr_b16 v[194:195], v220 offset:0x200
	ds_read_b64_tr_b16 v[196:197], v220 offset:0xa00
	ds_read_b64_tr_b16 v[214:215], v220 offset:0x1200
	ds_read_b64_tr_b16 v[216:217], v220 offset:0x1a00
	ds_read_b64_tr_b16 v[228:229], v220 offset:0x2200
	ds_read_b64_tr_b16 v[230:231], v220 offset:0x2a00
	ds_read_b64_tr_b16 v[232:233], v220 offset:0x3200
	ds_read_b64_tr_b16 v[234:235], v220 offset:0x3a00
	s_cbranch_vccnz .Lp0_nodma
	s_lshl_b32 s12, s9, 15
	s_add_i32 s12, s12, s7
	v_lshl_add_u64 v[238:239], s[38:39], 0, v[204:205]
	s_mov_b32 s13, m0
	s_mov_b32 m0, s12
	s_nop 0
	global_load_lds_dwordx4 v[238:239], off
	s_mov_b32 m0, s13
	v_lshl_add_u64 v[238:239], s[38:39], 0, v[206:207]
	s_add_i32 s13, s12, 0x400
	s_mov_b32 s24, m0
	s_mov_b32 m0, s13
	s_nop 0
	global_load_lds_dwordx4 v[238:239], off
	s_mov_b32 m0, s24
	v_lshl_add_u64 v[238:239], s[38:39], 0, v[208:209]
	s_add_i32 s13, s12, 0x800
	s_mov_b32 s24, m0
	s_mov_b32 m0, s13
	s_nop 0
	global_load_lds_dwordx4 v[238:239], off
	s_mov_b32 m0, s24
	v_lshl_add_u64 v[238:239], s[38:39], 0, v[210:211]
	s_addk_i32 s12, 0xc00
	s_mov_b32 s13, m0
	s_mov_b32 m0, s12
	s_nop 0
	global_load_lds_dwordx4 v[238:239], off
	s_mov_b32 m0, s13
.Lp0_nodma:
	s_waitcnt lgkmcnt(8)
	v_add_u32_e32 v221, 0x4000, v220
	v_mfma_f32_32x32x16_bf16 v[112:127], v[128:131], v[144:147], v[112:127]
	v_mfma_f32_32x32x16_bf16 v[112:127], v[132:135], v[148:151], v[112:127]
	v_mfma_f32_32x32x16_bf16 v[112:127], v[136:139], v[152:155], v[112:127]
	v_mfma_f32_32x32x16_bf16 v[112:127], v[140:143], v[156:159], v[112:127]
	ds_read_b64_tr_b16 v[144:145], v220 offset:0x400
	ds_read_b64_tr_b16 v[146:147], v220 offset:0xc00
	ds_read_b64_tr_b16 v[148:149], v220 offset:0x1400
	ds_read_b64_tr_b16 v[150:151], v220 offset:0x1c00
	ds_read_b64_tr_b16 v[152:153], v220 offset:0x2400
	ds_read_b64_tr_b16 v[154:155], v220 offset:0x2c00
	ds_read_b64_tr_b16 v[156:157], v220 offset:0x3400
	ds_read_b64_tr_b16 v[158:159], v220 offset:0x3c00
	s_waitcnt lgkmcnt(8)
	v_mfma_f32_32x32x16_bf16 v[96:111], v[128:131], v[194:197], v[96:111]
	v_mfma_f32_32x32x16_bf16 v[96:111], v[132:135], v[214:217], v[96:111]
	v_mfma_f32_32x32x16_bf16 v[96:111], v[136:139], v[228:231], v[96:111]
	v_mfma_f32_32x32x16_bf16 v[96:111], v[140:143], v[232:235], v[96:111]
	ds_read_b64_tr_b16 v[194:195], v220 offset:0x600
	ds_read_b64_tr_b16 v[196:197], v220 offset:0xe00
	ds_read_b64_tr_b16 v[214:215], v220 offset:0x1600
	ds_read_b64_tr_b16 v[216:217], v220 offset:0x1e00
	ds_read_b64_tr_b16 v[228:229], v220 offset:0x2600
	ds_read_b64_tr_b16 v[230:231], v220 offset:0x2e00
	ds_read_b64_tr_b16 v[232:233], v220 offset:0x3600
	ds_read_b64_tr_b16 v[234:235], v220 offset:0x3e00
	s_waitcnt lgkmcnt(8)
	v_mfma_f32_32x32x16_bf16 v[80:95], v[128:131], v[144:147], v[80:95]
	v_mfma_f32_32x32x16_bf16 v[80:95], v[132:135], v[148:151], v[80:95]
	v_mfma_f32_32x32x16_bf16 v[80:95], v[136:139], v[152:155], v[80:95]
	v_mfma_f32_32x32x16_bf16 v[80:95], v[140:143], v[156:159], v[80:95]
	ds_read_b64_tr_b16 v[144:145], v221 offset:0
	ds_read_b64_tr_b16 v[146:147], v221 offset:0x800
	ds_read_b64_tr_b16 v[148:149], v221 offset:0x1000
	ds_read_b64_tr_b16 v[150:151], v221 offset:0x1800
	ds_read_b64_tr_b16 v[152:153], v221 offset:0x2000
	ds_read_b64_tr_b16 v[154:155], v221 offset:0x2800
	ds_read_b64_tr_b16 v[156:157], v221 offset:0x3000
	ds_read_b64_tr_b16 v[158:159], v221 offset:0x3800
	s_waitcnt lgkmcnt(8)
	v_mfma_f32_32x32x16_bf16 v[64:79], v[128:131], v[194:197], v[64:79]
	v_mfma_f32_32x32x16_bf16 v[64:79], v[132:135], v[214:217], v[64:79]
	v_mfma_f32_32x32x16_bf16 v[64:79], v[136:139], v[228:231], v[64:79]
	v_mfma_f32_32x32x16_bf16 v[64:79], v[140:143], v[232:235], v[64:79]
	ds_read_b64_tr_b16 v[194:195], v221 offset:0x200
	ds_read_b64_tr_b16 v[196:197], v221 offset:0xa00
	ds_read_b64_tr_b16 v[214:215], v221 offset:0x1200
	ds_read_b64_tr_b16 v[216:217], v221 offset:0x1a00
	ds_read_b64_tr_b16 v[228:229], v221 offset:0x2200
	ds_read_b64_tr_b16 v[230:231], v221 offset:0x2a00
	ds_read_b64_tr_b16 v[232:233], v221 offset:0x3200
	ds_read_b64_tr_b16 v[234:235], v221 offset:0x3a00
	s_waitcnt lgkmcnt(8)
	v_mfma_f32_32x32x16_bf16 v[48:63], v[128:131], v[144:147], v[48:63]
	v_mfma_f32_32x32x16_bf16 v[48:63], v[132:135], v[148:151], v[48:63]
	v_mfma_f32_32x32x16_bf16 v[48:63], v[136:139], v[152:155], v[48:63]
	v_mfma_f32_32x32x16_bf16 v[48:63], v[140:143], v[156:159], v[48:63]
	ds_read_b64_tr_b16 v[144:145], v221 offset:0x400
	ds_read_b64_tr_b16 v[146:147], v221 offset:0xc00
	ds_read_b64_tr_b16 v[148:149], v221 offset:0x1400
	ds_read_b64_tr_b16 v[150:151], v221 offset:0x1c00
	ds_read_b64_tr_b16 v[152:153], v221 offset:0x2400
	ds_read_b64_tr_b16 v[154:155], v221 offset:0x2c00
	ds_read_b64_tr_b16 v[156:157], v221 offset:0x3400
	ds_read_b64_tr_b16 v[158:159], v221 offset:0x3c00
	s_waitcnt lgkmcnt(8)
	v_mfma_f32_32x32x16_bf16 v[32:47], v[128:131], v[194:197], v[32:47]
	v_mfma_f32_32x32x16_bf16 v[32:47], v[132:135], v[214:217], v[32:47]
	v_mfma_f32_32x32x16_bf16 v[32:47], v[136:139], v[228:231], v[32:47]
	v_mfma_f32_32x32x16_bf16 v[32:47], v[140:143], v[232:235], v[32:47]
	ds_read_b64_tr_b16 v[194:195], v221 offset:0x600
	ds_read_b64_tr_b16 v[196:197], v221 offset:0xe00
	ds_read_b64_tr_b16 v[214:215], v221 offset:0x1600
	ds_read_b64_tr_b16 v[216:217], v221 offset:0x1e00
	ds_read_b64_tr_b16 v[228:229], v221 offset:0x2600
	ds_read_b64_tr_b16 v[230:231], v221 offset:0x2e00
	ds_read_b64_tr_b16 v[232:233], v221 offset:0x3600
	ds_read_b64_tr_b16 v[234:235], v221 offset:0x3e00
	s_waitcnt lgkmcnt(8)
	v_mfma_f32_32x32x16_bf16 v[16:31], v[128:131], v[144:147], v[16:31]
	v_mfma_f32_32x32x16_bf16 v[16:31], v[132:135], v[148:151], v[16:31]
	v_mfma_f32_32x32x16_bf16 v[16:31], v[136:139], v[152:155], v[16:31]
	v_mfma_f32_32x32x16_bf16 v[16:31], v[140:143], v[156:159], v[16:31]
	s_waitcnt lgkmcnt(0)
	v_mfma_f32_32x32x16_bf16 v[0:15], v[128:131], v[194:197], v[0:15]
	s_mov_b64 s[24:25], -1
	s_and_b64 vcc, exec, s[90:91]
	v_mfma_f32_32x32x16_bf16 v[0:15], v[132:135], v[214:217], v[0:15]
	v_mfma_f32_32x32x16_bf16 v[0:15], v[136:139], v[228:231], v[0:15]
	v_mfma_f32_32x32x16_bf16 v[0:15], v[140:143], v[232:235], v[0:15]
	s_cbranch_vccz .LBB0_365
	s_waitcnt vmcnt(0) lgkmcnt(0)
	s_barrier
	s_mov_b64 s[24:25], 0

; #define A_WAITBAR(N) asm volatile("s_waitcnt vmcnt(" #N ") lgkmcnt(0) ; A256BAR\n\ts_barrier" ::: "memory")
; #define DMA_V(t, sl) do { const char* b_ = Vb + (size_t)(t) * TSTRIDE; const unsigned d_ = RFL(vdst + (sl) * 32768); glds16(b_ + voff[0], d_); glds16(b_ + voff[1], d_ + 1024); glds16(b_ + voff[2], d_ + 2048); glds16(b_ + voff[3], d_ + 3072); } while (0)
; template <int mode> ...
;     ...
;     if (more) A_WAITBAR(6); else A_WAITBAR(0);
;     if (more) DMA_V(j + 2, s2);
;     pv8(o, vb0 + s0 * 32768, pa0, pa1, pa2, pa3);
;     if (more) A_WAITBAR(6); else A_WAITBAR(0);
.Lp0_bar0:
	s_waitcnt vmcnt(0) lgkmcnt(0)
	s_barrier
	s_branch .LBB0_363

; __device__ __forceinline__ int crow(int r, int hi) { return (r & 3) + 8 * (r >> 2) + 4 * hi; }
; template <int mode> ...
;     ...
;   if (wid < 4) asm volatile("s_barrier" ::: "memory");
;   if (hi == 0) li_l[r32] = l_reg; asm volatile("s_waitcnt lgkmcnt(0)" ::: "memory");
;   float rli[16];
; #pragma unroll
;   for (int r = 0; r < 16; ++r) rli[r] = __builtin_amdgcn_rcpf(li_l[crow(r, hi)]);
;   typedef float f32x4_t __attribute__((ext_vector_type(4)));
;   f32x4_t* st4 = (f32x4_t*)stash + (size_t)wid * 2048 + lane;
;   if constexpr (mode == 0) {
; #pragma unroll
;     for (int d0 = 0; d0 < 8; ++d0)
; #pragma unroll
;       for (int q = 0; q < 4; ++q) st4[(d0 * 4 + q) * 64] = (f32x4_t){o[d0][4 * q] * rli[4 * q], o[d0][4 * q + 1] * rli[4 * q + 1], o[d0][4 * q + 2] * rli[4 * q + 2], o[d0][4 * q + 3] * rli[4 * q + 3]};
.LBB0_376:
	s_and_saveexec_b64 s[24:25], s[40:41]
	ds_write_b32 v201, v128
	s_or_b64 exec, exec, s[24:25]
	s_waitcnt lgkmcnt(0)
	v_add_u32_e32 v136, s8, v198
	ds_read_b128 v[128:131], v136
	ds_read_b128 v[132:135], v136 offset:32
	s_ashr_i32 s29, s28, 31
	s_lshl_b64 s[8:9], s[28:29], 15
	ds_read_b128 v[144:147], v136 offset:96
	s_waitcnt lgkmcnt(2)
	v_rcp_f32_e32 v142, v128
	v_rcp_f32_e32 v143, v129
	v_rcp_f32_e32 v140, v130
	v_rcp_f32_e32 v141, v131
	ds_read_b128 v[128:131], v136 offset:64
	s_waitcnt lgkmcnt(2)
	v_rcp_f32_e32 v132, v132
	v_rcp_f32_e32 v133, v133
	v_rcp_f32_e32 v138, v134
	v_rcp_f32_e32 v139, v135
	s_waitcnt lgkmcnt(0)
	v_rcp_f32_e32 v136, v128
	v_rcp_f32_e32 v137, v129
	v_rcp_f32_e32 v134, v130
	v_rcp_f32_e32 v135, v131
	v_readlane_b32 s0, v253, 46
	v_rcp_f32_e32 v130, v144
	v_rcp_f32_e32 v131, v145
	v_rcp_f32_e32 v128, v146
	v_rcp_f32_e32 v129, v147
	s_add_u32 s8, s0, s8
	v_readlane_b32 s0, v253, 47
	s_addc_u32 s9, s0, s9
	v_pk_mul_f32 v[112:113], v[112:113], v[142:143]
	v_pk_mul_f32 v[114:115], v[114:115], v[140:141]
	global_store_dwordx4 v200, v[112:115], s[8:9]
	v_mov_b32_e32 v201, v193
	v_lshl_add_u64 v[144:145], s[8:9], 0, v[200:201]
	v_pk_mul_f32 v[112:113], v[116:117], v[132:133]
	v_pk_mul_f32 v[114:115], v[118:119], v[138:139]
	global_store_dwordx4 v200, v[112:115], s[8:9] offset:1024
	s_movk_i32 s0, 0x1000
	v_pk_mul_f32 v[80:81], v[80:81], v[142:143]
	v_pk_mul_f32 v[112:113], v[120:121], v[136:137]
	v_pk_mul_f32 v[114:115], v[122:123], v[134:135]
	global_store_dwordx4 v200, v[112:115], s[8:9] offset:2048
	v_pk_mul_f32 v[82:83], v[82:83], v[140:141]
	v_pk_mul_f32 v[48:49], v[48:49], v[142:143]
	v_pk_mul_f32 v[112:113], v[124:125], v[130:131]
	v_pk_mul_f32 v[114:115], v[126:127], v[128:129]
	global_store_dwordx4 v200, v[112:115], s[8:9] offset:3072
	v_pk_mul_f32 v[50:51], v[50:51], v[140:141]
	v_pk_mul_f32 v[16:17], v[16:17], v[142:143]
	v_add_co_u32_e32 v112, vcc, s0, v144
	s_movk_i32 s0, 0x3000
	s_nop 0
	v_addc_co_u32_e32 v113, vcc, 0, v145, vcc
	v_add_co_u32_e32 v114, vcc, s15, v144
	v_pk_mul_f32 v[18:19], v[18:19], v[140:141]
	s_nop 0
	v_addc_co_u32_e32 v115, vcc, 0, v145, vcc
	global_store_dwordx4 v[114:115], v[80:83], off
	v_pk_mul_f32 v[96:97], v[96:97], v[142:143]
	v_pk_mul_f32 v[98:99], v[98:99], v[140:141]
	v_pk_mul_f32 v[80:81], v[84:85], v[132:133]
	v_pk_mul_f32 v[82:83], v[86:87], v[138:139]
	global_store_dwordx4 v[114:115], v[80:83], off offset:1024
	v_pk_mul_f32 v[64:65], v[64:65], v[142:143]
	v_pk_mul_f32 v[66:67], v[66:67], v[140:141]
	v_pk_mul_f32 v[80:81], v[88:89], v[136:137]
	v_pk_mul_f32 v[82:83], v[90:91], v[134:135]
	global_store_dwordx4 v[114:115], v[80:83], off offset:2048
	v_pk_mul_f32 v[32:33], v[32:33], v[142:143]
	v_pk_mul_f32 v[34:35], v[34:35], v[140:141]
	v_pk_mul_f32 v[80:81], v[92:93], v[130:131]
	v_pk_mul_f32 v[82:83], v[94:95], v[128:129]
	global_store_dwordx4 v[114:115], v[80:83], off offset:3072
	v_pk_mul_f32 v[0:1], v[0:1], v[142:143]
	v_pk_mul_f32 v[2:3], v[2:3], v[140:141]
	v_add_co_u32_e32 v80, vcc, s0, v144
	s_movk_i32 s0, 0x4000
	s_nop 0
	v_addc_co_u32_e32 v81, vcc, 0, v145, vcc
	v_add_co_u32_e32 v82, vcc, s0, v144
	s_movk_i32 s0, 0x5000
	s_nop 0
	v_addc_co_u32_e32 v83, vcc, 0, v145, vcc
	global_store_dwordx4 v[82:83], v[48:51], off
	global_store_dwordx4 v[114:115], v[96:99], off offset:-4096
	global_store_dwordx4 v[82:83], v[64:67], off offset:-4096
	v_pk_mul_f32 v[48:49], v[52:53], v[132:133]
	v_pk_mul_f32 v[50:51], v[54:55], v[138:139]
	global_store_dwordx4 v[82:83], v[48:51], off offset:1024
	v_pk_mul_f32 v[96:97], v[100:101], v[132:133]
	v_pk_mul_f32 v[98:99], v[102:103], v[138:139]
	v_pk_mul_f32 v[48:49], v[56:57], v[136:137]
	v_pk_mul_f32 v[50:51], v[58:59], v[134:135]
	global_store_dwordx4 v[82:83], v[48:51], off offset:2048
	v_pk_mul_f32 v[64:65], v[68:69], v[132:133]
	v_pk_mul_f32 v[66:67], v[70:71], v[138:139]
	v_pk_mul_f32 v[48:49], v[60:61], v[130:131]
	v_pk_mul_f32 v[50:51], v[62:63], v[128:129]
	global_store_dwordx4 v[82:83], v[48:51], off offset:3072
	global_store_dwordx4 v[112:113], v[96:99], off offset:1024
	global_store_dwordx4 v[80:81], v[64:67], off offset:1024
	v_add_co_u32_e32 v48, vcc, s0, v144
	s_movk_i32 s0, 0x7000
	s_nop 0
	v_addc_co_u32_e32 v49, vcc, 0, v145, vcc
	v_add_co_u32_e32 v50, vcc, s68, v144
	v_pk_mul_f32 v[96:97], v[104:105], v[136:137]
	s_nop 0
	v_addc_co_u32_e32 v51, vcc, 0, v145, vcc
	global_store_dwordx4 v[50:51], v[16:19], off
	global_store_dwordx4 v[50:51], v[32:35], off offset:-4096
	v_pk_mul_f32 v[98:99], v[106:107], v[134:135]
	v_pk_mul_f32 v[16:17], v[20:21], v[132:133]
	v_pk_mul_f32 v[18:19], v[22:23], v[138:139]
	global_store_dwordx4 v[50:51], v[16:19], off offset:1024
	v_pk_mul_f32 v[32:33], v[36:37], v[132:133]
	v_pk_mul_f32 v[34:35], v[38:39], v[138:139]
	v_pk_mul_f32 v[16:17], v[24:25], v[136:137]
	v_pk_mul_f32 v[18:19], v[26:27], v[134:135]
	global_store_dwordx4 v[50:51], v[16:19], off offset:2048
	v_pk_mul_f32 v[64:65], v[72:73], v[136:137]
	v_pk_mul_f32 v[66:67], v[74:75], v[134:135]
	v_pk_mul_f32 v[16:17], v[28:29], v[130:131]
	v_pk_mul_f32 v[18:19], v[30:31], v[128:129]
	global_store_dwordx4 v[50:51], v[16:19], off offset:3072
	global_store_dwordx4 v[48:49], v[32:35], off offset:1024
	global_store_dwordx4 v[112:113], v[96:99], off offset:2048
	v_add_co_u32_e32 v16, vcc, s0, v144
	v_pk_mul_f32 v[32:33], v[40:41], v[136:137]
	s_nop 0
	v_addc_co_u32_e32 v17, vcc, 0, v145, vcc
	global_store_dwordx4 v[16:17], v[0:3], off
	v_pk_mul_f32 v[34:35], v[42:43], v[134:135]
; #define A_WAITBAR(N) asm volatile("s_waitcnt vmcnt(" #N ") lgkmcnt(0) ; A256BAR\n\ts_barrier" ::: "memory")
; template <int mode> ...
;   asm volatile("" : "+v"(tid));
;   const int wid = __builtin_amdgcn_readfirstlane(tid >> 6), lane = tid & 63, r32 = lane & 31, hi = lane >> 5;
;   const unsigned lds0 = (unsigned)(uintptr_t)lds;
;   float* ws = (float*)(lds + A_LDS_WS) + wid * 64; float* li_l = ws; float* al_l = ws + 32;
;   unsigned koff[2], voff[4];
; #pragma unroll
;   for (int i = 0; i < 2; ++i) { const int row = (wid * 2 + i) * 4 + (lane >> 4), chunk = (lane & 15) ^ (((row & 7) << 1) | ((row >> 3) & 1)); koff[i] = (unsigned)(row * (LDP * 2) + chunk * 16); }
; #pragma unroll
;   for (int i = 0; i < 4; ++i) { const int q = (wid & 3) * 4 + i, subtile = q * 2 + (lane >> 5), kk = (subtile >> 2) * 8 + ((lane & 31) >> 2);
;     const int k = (kk & ~0xC) | ((kk & 4) << 1) | ((kk & 8) >> 1), col = (subtile & 3) * 32 + (lane & 3) * 8;
;     voff[i] = (unsigned)(k * (LDP * 2) + ((wid >> 2) * 128 + col) * 2); }
;   const char* Kb = (const char*)Kh; const char* Vb = (const char*)Vh;
;   const unsigned kdst = lds0 + A_LDS_K + wid * 2048, vdst = lds0 + A_LDS_V + (wid >> 2) * 16384 + (wid & 3) * 4096;
;     ...
;   bf16x8 qr[8];
;   { const hbf* Qw = Qb + (long)(wid * QBLK + r32) * LDQ + hi * 8;
; #pragma unroll
;     for (int d0 = 0; d0 < 8; ++d0) qr[d0] = *reinterpret_cast<const bf16x8*>(Qw + d0 * 16); }
;   asm volatile("" : "+v"(qr[0]), "+v"(qr[1]), "+v"(qr[2]), "+v"(qr[3]), "+v"(qr[4]), "+v"(qr[5]), "+v"(qr[6]), "+v"(qr[7]));
;   DMA_K(0, 0); DMA_V(0, 0); DMA_K(1, 1); DMA_V(1, 1);
;   float m_reg = 0.f, l_reg = 0; f32x16 o[8] = {};
;   const int vb0 = (int)(lds0 + A_LDS_V) + v_rd_base(lane);
;   const int kb0 = (int)(lds0 + A_LDS_K) + r32 * 256, kc = (hi << 4) ^ ((((r32 & 7) << 1) | ((r32 >> 3) & 1)) << 4);
;   const int NT = seq / KVBLK;
;     ...
;   A_WAITBAR(6);
;   if (wid >= 4) asm volatile("s_barrier" ::: "memory");
; __global__ void __launch_bounds__(NWAVES * 64, 2) mega_fwd(Args args) {
;     ...
;                 { const att::hbf* Qp = (const att::hbf*)(PROJ + qrow * LDP + C_DQ + (2 * h + 1) * 128);
;                   const att::hbf* Kp = (const att::hbf*)(PROJ + krow * LDP + C_DK + (2 * h + 1) * 128);
;                   att::attn256_unit<1>(Qp, Kp, Vp, SEQ, (char*)lds, CUR_TID(), stash, XB + qrow * DM + 2048 + h * 256, lam, subln_w); }
	v_pk_mul_f32 v[96:97], v[108:109], v[130:131]
	v_pk_mul_f32 v[0:1], v[4:5], v[132:133]
	v_pk_mul_f32 v[2:3], v[6:7], v[138:139]
	global_store_dwordx4 v[16:17], v[0:3], off offset:1024
	v_pk_mul_f32 v[98:99], v[110:111], v[128:129]
	global_store_dwordx4 v[80:81], v[64:67], off offset:2048
	v_pk_mul_f32 v[0:1], v[8:9], v[136:137]
	v_pk_mul_f32 v[2:3], v[10:11], v[134:135]
	v_pk_mul_f32 v[64:65], v[76:77], v[130:131]
	v_pk_mul_f32 v[66:67], v[78:79], v[128:129]
	global_store_dwordx4 v[48:49], v[32:35], off offset:2048
	global_store_dwordx4 v[16:17], v[0:3], off offset:2048
	global_store_dwordx4 v[112:113], v[96:99], off offset:3072
	v_pk_mul_f32 v[32:33], v[44:45], v[130:131]
	v_pk_mul_f32 v[34:35], v[46:47], v[128:129]
	v_pk_mul_f32 v[0:1], v[12:13], v[130:131]
	v_pk_mul_f32 v[2:3], v[14:15], v[128:129]
	global_store_dwordx4 v[80:81], v[64:67], off offset:3072
	global_store_dwordx4 v[48:49], v[32:35], off offset:3072
	global_store_dwordx4 v[16:17], v[0:3], off offset:3072
	s_or_b32 s0, s4, 0x100
	s_add_u32 s24, s5, s0
	v_mbcnt_lo_u32_b32 v0, -1, 0
	v_mbcnt_hi_u32_b32 v0, -1, v0
	s_addc_u32 s25, s6, 0
	v_add_u32_e32 v0, s59, v0
	v_mov_b64_e32 v[2:3], s[50:51]
	v_readfirstlane_b32 s6, v0
	s_ashr_i32 s38, s6, 6
	v_and_b32_e32 v250, 31, v0
	s_lshl_b32 s28, s38, 5
	v_bfe_u32 v213, v0, 5, 1
	v_or_b32_e32 v1, s28, v250
	v_mad_i64_i32 v[2:3], s[8:9], v1, s68, v[2:3]
	v_lshlrev_b32_e32 v198, 4, v213
	v_mov_b32_e32 v199, v193
	v_lshl_add_u64 v[2:3], v[2:3], 0, v[198:199]
	v_lshl_add_u64 v[2:3], v[2:3], 0, s[0:1]
	global_load_dwordx4 v[160:163], v[2:3], off offset:224
	global_load_dwordx4 v[164:167], v[2:3], off offset:192
	global_load_dwordx4 v[168:171], v[2:3], off offset:160
	global_load_dwordx4 v[172:175], v[2:3], off offset:128
	global_load_dwordx4 v[176:179], v[2:3], off offset:96
	global_load_dwordx4 v[180:183], v[2:3], off offset:64
	global_load_dwordx4 v[184:187], v[2:3], off offset:32
	global_load_dwordx4 v[188:191], v[2:3], off
	s_lshl_b32 s0, s38, 3
	v_bfe_u32 v1, v0, 4, 2
	v_and_b32_e32 v2, 15, v0
	s_and_b32 s5, s38, 1
	v_or_b32_e32 v3, s0, v1
	v_lshlrev_b32_e32 v4, 1, v1
	v_bitop3_b32 v4, v4, v2, s5 bitop3:0x36
	v_mul_lo_u32 v3, v3, s68
	v_or_b32_e32 v1, 4, v1
	v_lshl_or_b32 v192, v4, 4, v3
	v_or_b32_e32 v3, s0, v1
	v_lshlrev_b32_e32 v1, 1, v1
	v_bitop3_b32 v1, v1, v2, s5 bitop3:0x36
	v_mul_lo_u32 v2, v3, s68
	v_lshl_add_u32 v202, v1, 4, v2
	v_bfe_u32 v1, v0, 2, 3
	v_lshrrev_b32_e32 v2, 1, v0
	v_lshl_or_b32 v1, s38, 4, v1
	v_and_b32_e32 v2, 8, v2
	v_lshlrev_b32_e32 v199, 4, v0
	v_and_b32_e32 v1, 55, v1
	v_and_b32_e32 v2, 48, v199
	s_and_b32 s0, s6, 0xffffff00
	v_lshlrev_b32_e32 v3, 6, v213
	s_lshl_b32 s5, s6, 6
	s_lshl_b32 s7, s38, 12
	v_or3_b32 v2, s0, v2, v3
	s_lshl_b32 s0, s38, 11
	s_and_b32 s5, s5, 0xffffc000
	s_and_b32 s7, s7, 0x3000
	s_cmp_lg_u32 0, -1
	v_or_b32_e32 v3, 0x80, v2
	v_mov_b32_e32 v4, 0x30000
	s_cselect_b32 s8, 0, 0
	v_mad_u32_u24 v204, v1, s68, v2
	v_mad_u32_u24 v206, v1, s68, v3
	v_mad_u32_u24 v1, v1, s68, v4
	s_add_i32 s5, s8, s5
	v_add_u32_e32 v208, v1, v2
	v_add_u32_e32 v210, v1, v3
	s_add_i32 s0, s0, s8
	s_add_i32 s5, s5, s7
	s_waitcnt vmcnt(0)
	v_lshl_add_u64 v[2:3], s[24:25], 0, v[192:193]
	s_mov_b32 s7, m0
	s_mov_b32 m0, s0
	s_nop 0
	global_load_lds_dwordx4 v[2:3], off
	s_mov_b32 m0, s7
	v_mov_b32_e32 v203, v193
	v_lshl_add_u64 v[2:3], s[24:25], 0, v[202:203]
	s_add_i32 s7, s0, 0x400
	s_mov_b32 s8, m0
	s_mov_b32 m0, s7
	s_nop 0
	global_load_lds_dwordx4 v[2:3], off
	s_mov_b32 m0, s8
	v_mov_b32_e32 v205, v193
	s_add_i32 s5, s5, 0xc000
	v_lshl_add_u64 v[2:3], s[94:95], 0, v[204:205]
	s_mov_b32 s7, m0
	s_mov_b32 m0, s5
	s_nop 0
	global_load_lds_dwordx4 v[2:3], off
	s_mov_b32 m0, s7
	v_mov_b32_e32 v207, v193
	v_lshl_add_u64 v[2:3], s[94:95], 0, v[206:207]
	s_add_i32 s7, s5, 0x400
	s_mov_b32 s8, m0
	s_mov_b32 m0, s7
	s_nop 0
	global_load_lds_dwordx4 v[2:3], off
	s_mov_b32 m0, s8
	v_mov_b32_e32 v209, v193
	v_lshl_add_u64 v[2:3], s[94:95], 0, v[208:209]
	s_add_i32 s7, s5, 0x800
	s_mov_b32 s8, m0
	s_mov_b32 m0, s7
	s_nop 0
	global_load_lds_dwordx4 v[2:3], off
	s_mov_b32 m0, s8
	v_mov_b32_e32 v211, v193
	v_lshl_add_u64 v[2:3], s[94:95], 0, v[210:211]
	s_add_i32 s7, s5, 0xc00
	s_mov_b32 s8, m0
	s_mov_b32 m0, s7
	s_nop 0
	global_load_lds_dwordx4 v[2:3], off
	s_mov_b32 m0, s8
	s_add_u32 s8, s24, 0x180000
	s_addc_u32 s9, s25, 0
	s_add_i32 s7, s0, 0x4000
	v_lshl_add_u64 v[2:3], s[8:9], 0, v[192:193]
	s_mov_b32 s10, m0
	s_mov_b32 m0, s7
	s_nop 0
	global_load_lds_dwordx4 v[2:3], off
	s_mov_b32 m0, s10
	v_lshl_add_u64 v[2:3], s[8:9], 0, v[202:203]
	s_add_i32 s7, s0, 0x4400
	s_mov_b32 s8, m0
	s_mov_b32 m0, s7
	s_nop 0
	global_load_lds_dwordx4 v[2:3], off
	s_mov_b32 m0, s8
	s_add_i32 s7, s5, 0x8000
	v_lshl_add_u64 v[2:3], s[52:53], 0, v[204:205]
	s_mov_b32 s8, m0
	s_mov_b32 m0, s7
	s_nop 0
	global_load_lds_dwordx4 v[2:3], off
	s_mov_b32 m0, s8
	v_lshl_add_u64 v[2:3], s[52:53], 0, v[206:207]
	s_add_i32 s7, s5, 0x8400
	s_mov_b32 s8, m0
	s_mov_b32 m0, s7
	s_nop 0
	global_load_lds_dwordx4 v[2:3], off
	s_mov_b32 m0, s8
	v_lshl_add_u64 v[2:3], s[52:53], 0, v[208:209]
	s_add_i32 s7, s5, 0x8800
	s_mov_b32 s8, m0
	s_mov_b32 m0, s7
	s_nop 0
	global_load_lds_dwordx4 v[2:3], off
	s_mov_b32 m0, s8
	v_lshl_add_u64 v[2:3], s[52:53], 0, v[210:211]
	s_add_i32 s7, s5, 0x8c00
	s_mov_b32 s8, m0
	s_mov_b32 m0, s7
	s_nop 0
	global_load_lds_dwordx4 v[2:3], off
	s_mov_b32 m0, s8
	s_waitcnt vmcnt(6) lgkmcnt(0)
	s_barrier
	s_cmp_lt_i32 s38, 4
	s_cbranch_scc1 .LBB0_380
	s_barrier

; #define SBAR() __builtin_amdgcn_sched_barrier(0)
; #define KRD(A, B, d0) do { const int ad_ = (kc ^ ((d0) << 5)) + kbt; A = lds_rd128<0>(ad_); B = lds_rd128<8192>(ad_); } while (0)
; #define KW(N) do { asm volatile("s_waitcnt lgkmcnt(" #N ")" ::: "memory"); SBAR(); } while (0)
; #define DMA_K(t, sl) do { const char* b_ = Kb + (size_t)(t) * TSTRIDE; const unsigned d_ = RFL(kdst + (sl) * 16384); glds16(b_ + koff[0], d_); glds16(b_ + koff[1], d_ + 1024); } while (0)
; __device__ __forceinline__ void qkt_pipe(f32x16& p0, f32x16& p1, int kbt, int kc, const bf16x8* qr, const f32x16& z) {
;   bf16x8 a0, b0, a1, b1, a2, b2, a3, b3;
;     ...
;   KRD(a0, b0, 0); KRD(a1, b1, 1); KRD(a2, b2, 2); KRD(a3, b3, 3);
;   KW(6); p0 = __builtin_amdgcn_mfma_f32_32x32x16_bf16(a0, qr[0], z, 0, 0, 0);  p1 = __builtin_amdgcn_mfma_f32_32x32x16_bf16(b0, qr[0], z, 0, 0, 0);  SBAR(); KRD(a0, b0, 4);
;   KW(6); p0 = __builtin_amdgcn_mfma_f32_32x32x16_bf16(a1, qr[1], p0, 0, 0, 0); p1 = __builtin_amdgcn_mfma_f32_32x32x16_bf16(b1, qr[1], p1, 0, 0, 0); SBAR(); KRD(a1, b1, 5);
;   KW(6); p0 = __builtin_amdgcn_mfma_f32_32x32x16_bf16(a2, qr[2], p0, 0, 0, 0); p1 = __builtin_amdgcn_mfma_f32_32x32x16_bf16(b2, qr[2], p1, 0, 0, 0); SBAR(); KRD(a2, b2, 6);
;   KW(6); p0 = __builtin_amdgcn_mfma_f32_32x32x16_bf16(a3, qr[3], p0, 0, 0, 0); p1 = __builtin_amdgcn_mfma_f32_32x32x16_bf16(b3, qr[3], p1, 0, 0, 0); SBAR(); KRD(a3, b3, 7);
;   KW(6); p0 = __builtin_amdgcn_mfma_f32_32x32x16_bf16(a0, qr[4], p0, 0, 0, 0); p1 = __builtin_amdgcn_mfma_f32_32x32x16_bf16(b0, qr[4], p1, 0, 0, 0); SBAR();
;   KW(4); p0 = __builtin_amdgcn_mfma_f32_32x32x16_bf16(a1, qr[5], p0, 0, 0, 0); p1 = __builtin_amdgcn_mfma_f32_32x32x16_bf16(b1, qr[5], p1, 0, 0, 0); SBAR();
;   KW(2); p0 = __builtin_amdgcn_mfma_f32_32x32x16_bf16(a2, qr[6], p0, 0, 0, 0); p1 = __builtin_amdgcn_mfma_f32_32x32x16_bf16(b2, qr[6], p1, 0, 0, 0); SBAR();
;   KW(0); p0 = __builtin_amdgcn_mfma_f32_32x32x16_bf16(a3, qr[7], p0, 0, 0, 0); p1 = __builtin_amdgcn_mfma_f32_32x32x16_bf16(b3, qr[7], p1, 0, 0, 0);
; template <int mode> ...
;     ...
;   for (int j = 0; j < NT; ++j) {
;     const bool more = j + 2 < NT;
;     if (more) DMA_K(j + 2, s2);
;     f32x16 p0, p1; bf16x8 pa0, pa1, pa2, pa3;
;     __builtin_amdgcn_s_setprio(2);
;     { f32x16 negm;
; #pragma unroll
;       for (int r = 0; r < 16; ++r) negm[r] = -m_reg;
;       qkt_pipe(p0, p1, kb0 + s0 * 16384, kc, qr, negm); }
.LBB0_381:
	s_mov_b32 s10, s11
	s_add_i32 s11, s9, 2
	s_cmp_lt_u32 s11, s74
	s_cselect_b64 s[52:53], -1, 0
	s_cmp_ge_u32 s11, s74
	s_cselect_b64 s[50:51], -1, 0
	s_and_b64 vcc, exec, s[50:51]
	s_setprio 2
	v_lshl_add_u32 v212, s10, 14, v201
	v_add_u32_e32 v144, v212, v225
	ds_read_b128 v[194:197], v144 offset:0
	ds_read_b128 v[214:217], v144 offset:0x2000
	v_xor_b32_e32 v144, 32, v225
	v_add_u32_e32 v144, v212, v144
	ds_read_b128 v[230:233], v144 offset:0
	ds_read_b128 v[234:237], v144 offset:0x2000
	v_xor_b32_e32 v144, 64, v225
	v_add_u32_e32 v144, v212, v144
	ds_read_b128 v[238:241], v144 offset:0
	ds_read_b128 v[242:245], v144 offset:0x2000
	v_xor_b32_e32 v144, 0x60, v225
	v_add_u32_e32 v144, v212, v144
	ds_read_b128 v[246:249], v144 offset:0
	ds_read_b128 v[220:223], v144 offset:0x2000
	s_cbranch_vccnz .Lq1_nodma
	s_add_u32 s24, s60, 0xfffff100
	s_addc_u32 s25, s61, -1
	s_lshl_b32 s11, s7, 14
	s_add_i32 s11, s11, s0
	v_lshl_add_u64 v[128:129], s[24:25], 0, v[192:193]
	s_mov_b32 s12, m0
	s_mov_b32 m0, s11
	s_nop 0
	global_load_lds_dwordx4 v[128:129], off
	s_mov_b32 m0, s12
	v_lshl_add_u64 v[128:129], s[24:25], 0, v[202:203]
	s_addk_i32 s11, 0x400
	s_mov_b32 s12, m0
	s_mov_b32 m0, s11
	s_nop 0
	global_load_lds_dwordx4 v[128:129], off
	s_mov_b32 m0, s12
.Lq1_nodma:
	s_waitcnt lgkmcnt(6)
	v_xor_b32_e32 v128, 0x80000000, v227
	v_mov_b32_e32 v129, v128
	v_mov_b32_e32 v130, v128
	v_mov_b32_e32 v131, v128
	v_mov_b32_e32 v132, v128
	v_mov_b32_e32 v133, v128
	v_mov_b32_e32 v134, v128
	v_mov_b32_e32 v135, v128
	v_mov_b32_e32 v136, v128
	v_mov_b32_e32 v137, v128
	v_mov_b32_e32 v138, v128
	v_mov_b32_e32 v139, v128
	v_mov_b32_e32 v140, v128
	v_mov_b32_e32 v141, v128
	v_mov_b32_e32 v142, v128
	v_mov_b32_e32 v143, v128
	s_nop 1
	v_mfma_f32_32x32x16_bf16 v[144:159], v[194:197], v[188:191], v[128:143]
	v_mfma_f32_32x32x16_bf16 v[128:143], v[214:217], v[188:191], v[128:143]
	v_xor_b32_e32 v194, 0x80, v225
	v_add_u32_e32 v229, v212, v194
	ds_read_b128 v[194:197], v229 offset:0
	ds_read_b128 v[214:217], v229 offset:0x2000
	s_waitcnt lgkmcnt(6)
	v_mfma_f32_32x32x16_bf16 v[144:159], v[230:233], v[184:187], v[144:159]
	v_mfma_f32_32x32x16_bf16 v[128:143], v[234:237], v[184:187], v[128:143]
	v_xor_b32_e32 v229, 0xa0, v225
	v_add_u32_e32 v229, v212, v229
	ds_read_b128 v[230:233], v229 offset:0
	ds_read_b128 v[234:237], v229 offset:0x2000
	s_waitcnt lgkmcnt(6)
	v_mfma_f32_32x32x16_bf16 v[144:159], v[238:241], v[180:183], v[144:159]
	v_mfma_f32_32x32x16_bf16 v[128:143], v[242:245], v[180:183], v[128:143]
	v_xor_b32_e32 v229, 0xc0, v225
	v_add_u32_e32 v229, v212, v229
	ds_read_b128 v[238:241], v229 offset:0
	ds_read_b128 v[242:245], v229 offset:0x2000
	s_waitcnt lgkmcnt(6)
	v_mfma_f32_32x32x16_bf16 v[144:159], v[246:249], v[176:179], v[144:159]
	v_mfma_f32_32x32x16_bf16 v[128:143], v[220:223], v[176:179], v[128:143]
	v_xor_b32_e32 v220, 0xe0, v225
	v_add_u32_e32 v212, v212, v220
	ds_read_b128 v[220:223], v212 offset:0
	ds_read_b128 v[246:249], v212 offset:0x2000
	s_waitcnt lgkmcnt(6)
	v_mfma_f32_32x32x16_bf16 v[144:159], v[194:197], v[172:175], v[144:159]
	v_mfma_f32_32x32x16_bf16 v[128:143], v[214:217], v[172:175], v[128:143]
	s_waitcnt lgkmcnt(4)
	v_mfma_f32_32x32x16_bf16 v[144:159], v[230:233], v[168:171], v[144:159]
	v_mfma_f32_32x32x16_bf16 v[128:143], v[234:237], v[168:171], v[128:143]
	s_waitcnt lgkmcnt(2)
	v_mfma_f32_32x32x16_bf16 v[144:159], v[238:241], v[164:167], v[144:159]
	v_mfma_f32_32x32x16_bf16 v[128:143], v[242:245], v[164:167], v[128:143]
	s_waitcnt lgkmcnt(0)
	v_mfma_f32_32x32x16_bf16 v[144:159], v[220:223], v[160:163], v[144:159]
	s_cmp_eq_u32 s9, 0
	s_cselect_b64 s[56:57], -1, 0
	s_cmp_lg_u32 s9, 0
	v_mfma_f32_32x32x16_bf16 v[128:143], v[246:249], v[160:163], v[128:143]
	s_nop 7
	v_max_f32_e32 v194, v145, v145
	v_max_f32_e32 v195, v144, v144
	v_max_f32_e32 v194, v195, v194
	v_max3_f32 v194, v194, v146, v147
	v_max3_f32 v194, v194, v148, v149
	v_max3_f32 v194, v194, v150, v151
	v_max3_f32 v194, v194, v152, v153
	v_max3_f32 v194, v194, v154, v155
	v_max3_f32 v194, v194, v156, v157
	v_max3_f32 v194, v194, v158, v159
	v_max3_f32 v194, v194, v128, v129
	v_max3_f32 v194, v194, v130, v131
	v_max3_f32 v194, v194, v132, v133
	v_max3_f32 v194, v194, v134, v135
	v_max3_f32 v194, v194, v136, v137
	v_max3_f32 v194, v194, v138, v139
	v_max3_f32 v194, v194, v140, v141
	v_max3_f32 v194, v194, v142, v143
	v_mov_b32_e32 v195, v194
	s_nop 1
	v_permlane32_swap_b32_e32 v194, v195
	v_max_f32_e32 v195, v195, v195
	v_max_f32_e32 v194, v194, v194
	v_max_f32_e32 v229, v194, v195
	s_cbranch_scc0 .LBB0_404
	v_cmp_lt_f32_e32 vcc, s30, v229
	s_mov_b64 s[24:25], 0
	s_mov_b64 s[62:63], 0
	s_cbranch_vccnz .LBB0_405
	s_and_b64 vcc, exec, s[24:25]
	s_cbranch_vccnz .LBB0_406

; __device__ __forceinline__ float softmax_rel(f32x16& p0, f32x16& p1, bool first, float& m_reg, float& l_reg, bf16x8& pa0, bf16x8& pa1, bf16x8& pa2, bf16x8& pa3) {
;     ...
; #pragma unroll
;   for (int r = 0; r < 16; ++r) p0[r] = __builtin_amdgcn_exp2f(p0[r]);
; #pragma unroll
;   for (int r = 0; r < 16; ++r) p1[r] = __builtin_amdgcn_exp2f(p1[r]);
;   float ps = 0;
; #pragma unroll
;   for (int r = 0; r < 16; ++r) ps += p0[r];
; #pragma unroll
;   for (int r = 0; r < 16; ++r) ps += p1[r];
;   { auto rr = __builtin_amdgcn_permlane32_swap(__float_as_uint(ps), __float_as_uint(ps), false, false);
;     ps = __uint_as_float(rr[0]) + __uint_as_float(rr[1]); }
;   l_reg = l_reg * alpha + ps;
;   PK4(p0, 0, pa0); PK4(p0, 8, pa1); PK4(p1, 0, pa2); PK4(p1, 8, pa3);
;   return alpha;
.LBB0_388:
	v_exp_f32_e32 v144, v144
	v_exp_f32_e32 v145, v145
	v_exp_f32_e32 v146, v146
	v_exp_f32_e32 v147, v147
	v_exp_f32_e32 v148, v148
	v_exp_f32_e32 v194, v128
	v_add_f32_e32 v128, 0, v144
	v_exp_f32_e32 v149, v149
	v_add_f32_e32 v128, v145, v128
	v_exp_f32_e32 v150, v150
	v_add_f32_e32 v128, v146, v128
	v_exp_f32_e32 v151, v151
	v_add_f32_e32 v128, v147, v128
	v_exp_f32_e32 v152, v152
	v_add_f32_e32 v128, v148, v128
	v_exp_f32_e32 v153, v153
	v_add_f32_e32 v128, v149, v128
	v_exp_f32_e32 v154, v154
	v_add_f32_e32 v128, v150, v128
	v_exp_f32_e32 v155, v155
	v_add_f32_e32 v128, v151, v128
	v_exp_f32_e32 v156, v156
	v_add_f32_e32 v128, v152, v128
	v_exp_f32_e32 v157, v157
	v_add_f32_e32 v128, v153, v128
	v_exp_f32_e32 v158, v158
	v_add_f32_e32 v128, v154, v128
	v_exp_f32_e32 v159, v159
	v_add_f32_e32 v128, v155, v128
	v_add_f32_e32 v128, v156, v128
	v_exp_f32_e32 v195, v129
	v_add_f32_e32 v128, v157, v128
	v_exp_f32_e32 v196, v130
	v_add_f32_e32 v128, v158, v128
	v_exp_f32_e32 v197, v131
	v_add_f32_e32 v128, v159, v128
	v_exp_f32_e32 v214, v132
	v_add_f32_e32 v128, v194, v128
	v_exp_f32_e32 v215, v133
	v_add_f32_e32 v128, v195, v128
	v_exp_f32_e32 v216, v134
	v_add_f32_e32 v128, v196, v128
	v_exp_f32_e32 v217, v135
	v_add_f32_e32 v128, v197, v128
	v_exp_f32_e32 v220, v136
	v_add_f32_e32 v128, v214, v128
	v_exp_f32_e32 v221, v137
	v_add_f32_e32 v128, v215, v128
	v_exp_f32_e32 v222, v138
	v_add_f32_e32 v128, v216, v128
	v_exp_f32_e32 v223, v139
	v_add_f32_e32 v128, v217, v128
	v_exp_f32_e32 v231, v140
	v_add_f32_e32 v128, v220, v128
	v_exp_f32_e32 v232, v141
	v_add_f32_e32 v128, v221, v128
	v_exp_f32_e32 v233, v142
	v_add_f32_e32 v128, v222, v128
	v_exp_f32_e32 v143, v143
	v_add_f32_e32 v128, v223, v128
	v_add_f32_e32 v128, v231, v128
	v_add_f32_e32 v128, v232, v128
	v_add_f32_e32 v128, v233, v128
	v_add_f32_e32 v212, v143, v128
	v_mov_b32_e32 v230, v212
	v_cvt_pk_bf16_f32 v128, v144, v145
	v_cvt_pk_bf16_f32 v129, v146, v147
	v_cvt_pk_bf16_f32 v130, v148, v149
	v_cvt_pk_bf16_f32 v131, v150, v151
	v_cvt_pk_bf16_f32 v132, v152, v153
	v_cvt_pk_bf16_f32 v133, v154, v155
	v_cvt_pk_bf16_f32 v134, v156, v157
	v_cvt_pk_bf16_f32 v135, v158, v159
	v_cvt_pk_bf16_f32 v136, v194, v195
	v_cvt_pk_bf16_f32 v137, v196, v197
	v_cvt_pk_bf16_f32 v138, v214, v215
	v_cvt_pk_bf16_f32 v139, v216, v217
	v_cvt_pk_bf16_f32 v140, v220, v221
	v_cvt_pk_bf16_f32 v141, v222, v223
	v_cvt_pk_bf16_f32 v142, v231, v232
	v_cvt_pk_bf16_f32 v143, v233, v143
	s_nop 1
	v_permlane32_swap_b32_e32 v212, v230
	v_cmp_gt_f32_e32 vcc, 1.0, v229
	s_cbranch_vccz .LBB0_392
	s_and_saveexec_b64 s[24:25], s[40:41]
	ds_write_b32 v224, v229 offset:128
	s_or_b64 exec, exec, s[24:25]
	s_waitcnt lgkmcnt(0)
	v_add_u32_e32 v144, s6, v198
	ds_read_b128 v[156:159], v144 offset:224
	ds_read_b128 v[152:155], v144 offset:192
	ds_read_b128 v[148:151], v144 offset:160
	ds_read_b128 v[144:147], v144 offset:128
	s_waitcnt lgkmcnt(3)
	v_pk_mul_f32 v[28:29], v[28:29], v[156:157]
	s_waitcnt lgkmcnt(2)
	v_pk_mul_f32 v[24:25], v[24:25], v[152:153]
	s_waitcnt lgkmcnt(1)
	v_pk_mul_f32 v[20:21], v[20:21], v[148:149]
	v_pk_mul_f32 v[30:31], v[30:31], v[158:159]
	v_pk_mul_f32 v[26:27], v[26:27], v[154:155]
	v_pk_mul_f32 v[22:23], v[22:23], v[150:151]
	s_waitcnt lgkmcnt(0)
	v_pk_mul_f32 v[18:19], v[18:19], v[146:147]
	v_pk_mul_f32 v[16:17], v[16:17], v[144:145]
	v_pk_mul_f32 v[44:45], v[44:45], v[156:157]
	v_pk_mul_f32 v[40:41], v[40:41], v[152:153]
	v_pk_mul_f32 v[36:37], v[36:37], v[148:149]
	v_pk_mul_f32 v[46:47], v[46:47], v[158:159]
	v_pk_mul_f32 v[42:43], v[42:43], v[154:155]
	v_pk_mul_f32 v[38:39], v[38:39], v[150:151]
	v_pk_mul_f32 v[34:35], v[34:35], v[146:147]
	v_pk_mul_f32 v[32:33], v[32:33], v[144:145]
	v_pk_mul_f32 v[108:109], v[108:109], v[156:157]
	v_pk_mul_f32 v[104:105], v[104:105], v[152:153]
	v_pk_mul_f32 v[100:101], v[100:101], v[148:149]
	v_pk_mul_f32 v[110:111], v[110:111], v[158:159]
	v_pk_mul_f32 v[106:107], v[106:107], v[154:155]
	v_pk_mul_f32 v[102:103], v[102:103], v[150:151]
	v_pk_mul_f32 v[98:99], v[98:99], v[146:147]
	v_pk_mul_f32 v[96:97], v[96:97], v[144:145]
	v_pk_mul_f32 v[124:125], v[124:125], v[156:157]
	v_pk_mul_f32 v[120:121], v[120:121], v[152:153]
	v_pk_mul_f32 v[116:117], v[116:117], v[148:149]
	v_pk_mul_f32 v[126:127], v[126:127], v[158:159]
	v_pk_mul_f32 v[122:123], v[122:123], v[154:155]
	v_pk_mul_f32 v[118:119], v[118:119], v[150:151]
	v_pk_mul_f32 v[114:115], v[114:115], v[146:147]
	v_pk_mul_f32 v[112:113], v[112:113], v[144:145]
	v_pk_mul_f32 v[76:77], v[76:77], v[156:157]
	v_pk_mul_f32 v[72:73], v[72:73], v[152:153]
	v_pk_mul_f32 v[68:69], v[68:69], v[148:149]
	v_pk_mul_f32 v[78:79], v[78:79], v[158:159]
	v_pk_mul_f32 v[74:75], v[74:75], v[154:155]
	v_pk_mul_f32 v[70:71], v[70:71], v[150:151]
	v_pk_mul_f32 v[66:67], v[66:67], v[146:147]
	v_pk_mul_f32 v[64:65], v[64:65], v[144:145]
	v_pk_mul_f32 v[60:61], v[60:61], v[156:157]
	v_pk_mul_f32 v[56:57], v[56:57], v[152:153]
	v_pk_mul_f32 v[52:53], v[52:53], v[148:149]
	v_pk_mul_f32 v[62:63], v[62:63], v[158:159]
	v_pk_mul_f32 v[58:59], v[58:59], v[154:155]
	v_pk_mul_f32 v[54:55], v[54:55], v[150:151]
	v_pk_mul_f32 v[50:51], v[50:51], v[146:147]
	v_pk_mul_f32 v[48:49], v[48:49], v[144:145]
	v_pk_mul_f32 v[12:13], v[12:13], v[156:157]
	v_pk_mul_f32 v[8:9], v[8:9], v[152:153]
	v_pk_mul_f32 v[4:5], v[4:5], v[148:149]
	v_pk_mul_f32 v[14:15], v[14:15], v[158:159]
	v_pk_mul_f32 v[10:11], v[10:11], v[154:155]
	v_pk_mul_f32 v[6:7], v[6:7], v[150:151]
	v_pk_mul_f32 v[2:3], v[2:3], v[146:147]
	v_pk_mul_f32 v[0:1], v[0:1], v[144:145]
	v_pk_mul_f32 v[92:93], v[92:93], v[156:157]
	v_pk_mul_f32 v[88:89], v[88:89], v[152:153]
	v_pk_mul_f32 v[84:85], v[84:85], v[148:149]
	v_pk_mul_f32 v[94:95], v[94:95], v[158:159]
	v_pk_mul_f32 v[90:91], v[90:91], v[154:155]
	v_pk_mul_f32 v[86:87], v[86:87], v[150:151]
	v_pk_mul_f32 v[82:83], v[82:83], v[146:147]
	v_pk_mul_f32 v[80:81], v[80:81], v[144:145]
; #define SBAR() __builtin_amdgcn_sched_barrier(0)
; #define VF_WAIT(N) do { asm volatile("s_waitcnt lgkmcnt(" #N ")" ::: "memory"); SBAR(); } while (0)
; #define A_WAITBAR(N) asm volatile("s_waitcnt vmcnt(" #N ") lgkmcnt(0) ; A256BAR\n\ts_barrier" ::: "memory")
; #define DMA_V(t, sl) do { const char* b_ = Vb + (size_t)(t) * TSTRIDE; const unsigned d_ = RFL(vdst + (sl) * 32768); glds16(b_ + voff[0], d_); glds16(b_ + voff[1], d_ + 1024); glds16(b_ + voff[2], d_ + 2048); glds16(b_ + voff[3], d_ + 3072); } while (0)
; __device__ __forceinline__ void pv8(f32x16* o, int vb, bf16x8 pa0, bf16x8 pa1, bf16x8 pa2, bf16x8 pa3) {
;   VFrag fa, fb; const int vb2 = vb + 16384;
;   vf_read<0>(fa, vb);
;   vf_read<1>(fb, vb);  VF_WAIT(8); vf_mma(o[0], fa, pa0, pa1, pa2, pa3); SBAR();
;   vf_read<2>(fa, vb);  VF_WAIT(8); vf_mma(o[1], fb, pa0, pa1, pa2, pa3); SBAR();
;   vf_read<3>(fb, vb);  VF_WAIT(8); vf_mma(o[2], fa, pa0, pa1, pa2, pa3); SBAR();
;   vf_read<0>(fa, vb2); VF_WAIT(8); vf_mma(o[3], fb, pa0, pa1, pa2, pa3); SBAR();
;   vf_read<1>(fb, vb2); VF_WAIT(8); vf_mma(o[4], fa, pa0, pa1, pa2, pa3); SBAR();
;   vf_read<2>(fa, vb2); VF_WAIT(8); vf_mma(o[5], fb, pa0, pa1, pa2, pa3); SBAR();
;   vf_read<3>(fb, vb2); VF_WAIT(8); vf_mma(o[6], fa, pa0, pa1, pa2, pa3); SBAR();
;   VF_WAIT(0); vf_mma(o[7], fb, pa0, pa1, pa2, pa3);
; }
; template <int mode> ...
;     ...
;     __builtin_amdgcn_s_setprio(0);
;     if (more) A_WAITBAR(6); else A_WAITBAR(0);
;     if (more) DMA_V(j + 2, s2);
;     pv8(o, vb0 + s0 * 32768, pa0, pa1, pa2, pa3);
;     if (more) A_WAITBAR(6); else A_WAITBAR(0);
.LBB0_392:
	s_setprio 0
	s_and_b64 vcc, exec, s[50:51]
	s_cbranch_vccnz .Lp1_bar0
	s_waitcnt vmcnt(6) lgkmcnt(0)
	s_barrier
.LBB0_396:
	v_lshl_add_u32 v231, s10, 15, v226
	ds_read_b64_tr_b16 v[144:145], v231 offset:0
	ds_read_b64_tr_b16 v[146:147], v231 offset:0x800
	ds_read_b64_tr_b16 v[148:149], v231 offset:0x1000
	ds_read_b64_tr_b16 v[150:151], v231 offset:0x1800
	ds_read_b64_tr_b16 v[152:153], v231 offset:0x2000
	ds_read_b64_tr_b16 v[154:155], v231 offset:0x2800
	ds_read_b64_tr_b16 v[156:157], v231 offset:0x3000
	ds_read_b64_tr_b16 v[158:159], v231 offset:0x3800
	ds_read_b64_tr_b16 v[194:195], v231 offset:0x200
	ds_read_b64_tr_b16 v[196:197], v231 offset:0xa00
	ds_read_b64_tr_b16 v[214:215], v231 offset:0x1200
	ds_read_b64_tr_b16 v[216:217], v231 offset:0x1a00
	ds_read_b64_tr_b16 v[220:221], v231 offset:0x2200
	ds_read_b64_tr_b16 v[222:223], v231 offset:0x2a00
	ds_read_b64_tr_b16 v[232:233], v231 offset:0x3200
	ds_read_b64_tr_b16 v[234:235], v231 offset:0x3a00
	s_cbranch_vccnz .Lp1_nodma
	s_lshl_b32 s11, s7, 15
	s_add_i32 s11, s11, s5
	v_lshl_add_u64 v[238:239], s[60:61], 0, v[204:205]
	s_mov_b32 s12, m0
	s_mov_b32 m0, s11
	s_nop 0
	global_load_lds_dwordx4 v[238:239], off
	s_mov_b32 m0, s12
	v_lshl_add_u64 v[238:239], s[60:61], 0, v[206:207]
	s_add_i32 s12, s11, 0x400
	s_mov_b32 s13, m0
	s_mov_b32 m0, s12
	s_nop 0
	global_load_lds_dwordx4 v[238:239], off
	s_mov_b32 m0, s13
	v_lshl_add_u64 v[238:239], s[60:61], 0, v[208:209]
	s_add_i32 s12, s11, 0x800
	s_mov_b32 s13, m0
	s_mov_b32 m0, s12
	s_nop 0
	global_load_lds_dwordx4 v[238:239], off
	s_mov_b32 m0, s13
	v_lshl_add_u64 v[238:239], s[60:61], 0, v[210:211]
	s_addk_i32 s11, 0xc00
	s_mov_b32 s12, m0
	s_mov_b32 m0, s11
	s_nop 0
	global_load_lds_dwordx4 v[238:239], off
	s_mov_b32 m0, s12
.Lp1_nodma:
	s_waitcnt lgkmcnt(8)
	v_add_u32_e32 v236, 0x4000, v231
	v_mfma_f32_32x32x16_bf16 v[16:31], v[128:131], v[144:147], v[16:31]
	v_mfma_f32_32x32x16_bf16 v[16:31], v[132:135], v[148:151], v[16:31]
	v_mfma_f32_32x32x16_bf16 v[16:31], v[136:139], v[152:155], v[16:31]
	v_mfma_f32_32x32x16_bf16 v[16:31], v[140:143], v[156:159], v[16:31]
	ds_read_b64_tr_b16 v[144:145], v231 offset:0x400
	ds_read_b64_tr_b16 v[146:147], v231 offset:0xc00
	ds_read_b64_tr_b16 v[148:149], v231 offset:0x1400
	ds_read_b64_tr_b16 v[150:151], v231 offset:0x1c00
	ds_read_b64_tr_b16 v[152:153], v231 offset:0x2400
	ds_read_b64_tr_b16 v[154:155], v231 offset:0x2c00
	ds_read_b64_tr_b16 v[156:157], v231 offset:0x3400
	ds_read_b64_tr_b16 v[158:159], v231 offset:0x3c00
	s_waitcnt lgkmcnt(8)
	v_mfma_f32_32x32x16_bf16 v[32:47], v[128:131], v[194:197], v[32:47]
	v_mfma_f32_32x32x16_bf16 v[32:47], v[132:135], v[214:217], v[32:47]
	v_mfma_f32_32x32x16_bf16 v[32:47], v[136:139], v[220:223], v[32:47]
	v_mfma_f32_32x32x16_bf16 v[32:47], v[140:143], v[232:235], v[32:47]
	ds_read_b64_tr_b16 v[194:195], v231 offset:0x600
	ds_read_b64_tr_b16 v[196:197], v231 offset:0xe00
	ds_read_b64_tr_b16 v[214:215], v231 offset:0x1600
	ds_read_b64_tr_b16 v[216:217], v231 offset:0x1e00
	ds_read_b64_tr_b16 v[220:221], v231 offset:0x2600
	ds_read_b64_tr_b16 v[222:223], v231 offset:0x2e00
	ds_read_b64_tr_b16 v[232:233], v231 offset:0x3600
	ds_read_b64_tr_b16 v[234:235], v231 offset:0x3e00
	s_waitcnt lgkmcnt(8)
	v_mfma_f32_32x32x16_bf16 v[96:111], v[128:131], v[144:147], v[96:111]
	v_mfma_f32_32x32x16_bf16 v[96:111], v[132:135], v[148:151], v[96:111]
	v_mfma_f32_32x32x16_bf16 v[96:111], v[136:139], v[152:155], v[96:111]
	v_mfma_f32_32x32x16_bf16 v[96:111], v[140:143], v[156:159], v[96:111]
	ds_read_b64_tr_b16 v[144:145], v236 offset:0
	ds_read_b64_tr_b16 v[146:147], v236 offset:0x800
	ds_read_b64_tr_b16 v[148:149], v236 offset:0x1000
	ds_read_b64_tr_b16 v[150:151], v236 offset:0x1800
	ds_read_b64_tr_b16 v[152:153], v236 offset:0x2000
	ds_read_b64_tr_b16 v[154:155], v236 offset:0x2800
	ds_read_b64_tr_b16 v[156:157], v236 offset:0x3000
	ds_read_b64_tr_b16 v[158:159], v236 offset:0x3800
	s_waitcnt lgkmcnt(8)
	v_mfma_f32_32x32x16_bf16 v[112:127], v[128:131], v[194:197], v[112:127]
	v_mfma_f32_32x32x16_bf16 v[112:127], v[132:135], v[214:217], v[112:127]
	v_mfma_f32_32x32x16_bf16 v[112:127], v[136:139], v[220:223], v[112:127]
	v_mfma_f32_32x32x16_bf16 v[112:127], v[140:143], v[232:235], v[112:127]
	ds_read_b64_tr_b16 v[194:195], v236 offset:0x200
	ds_read_b64_tr_b16 v[196:197], v236 offset:0xa00
	ds_read_b64_tr_b16 v[214:215], v236 offset:0x1200
	ds_read_b64_tr_b16 v[216:217], v236 offset:0x1a00
	ds_read_b64_tr_b16 v[220:221], v236 offset:0x2200
	ds_read_b64_tr_b16 v[222:223], v236 offset:0x2a00
	ds_read_b64_tr_b16 v[232:233], v236 offset:0x3200
	ds_read_b64_tr_b16 v[234:235], v236 offset:0x3a00
	s_waitcnt lgkmcnt(8)
	v_mfma_f32_32x32x16_bf16 v[64:79], v[128:131], v[144:147], v[64:79]
	v_mfma_f32_32x32x16_bf16 v[64:79], v[132:135], v[148:151], v[64:79]
	v_mfma_f32_32x32x16_bf16 v[64:79], v[136:139], v[152:155], v[64:79]
	v_mfma_f32_32x32x16_bf16 v[64:79], v[140:143], v[156:159], v[64:79]
	ds_read_b64_tr_b16 v[144:145], v236 offset:0x400
	ds_read_b64_tr_b16 v[146:147], v236 offset:0xc00
	ds_read_b64_tr_b16 v[148:149], v236 offset:0x1400
	ds_read_b64_tr_b16 v[150:151], v236 offset:0x1c00
	ds_read_b64_tr_b16 v[152:153], v236 offset:0x2400
	ds_read_b64_tr_b16 v[154:155], v236 offset:0x2c00
	ds_read_b64_tr_b16 v[156:157], v236 offset:0x3400
	ds_read_b64_tr_b16 v[158:159], v236 offset:0x3c00
	s_waitcnt lgkmcnt(8)
	v_mfma_f32_32x32x16_bf16 v[48:63], v[128:131], v[194:197], v[48:63]
	v_mfma_f32_32x32x16_bf16 v[48:63], v[132:135], v[214:217], v[48:63]
	v_mfma_f32_32x32x16_bf16 v[48:63], v[136:139], v[220:223], v[48:63]
	v_mfma_f32_32x32x16_bf16 v[48:63], v[140:143], v[232:235], v[48:63]
	ds_read_b64_tr_b16 v[194:195], v236 offset:0x600
	ds_read_b64_tr_b16 v[196:197], v236 offset:0xe00
	ds_read_b64_tr_b16 v[214:215], v236 offset:0x1600
	ds_read_b64_tr_b16 v[216:217], v236 offset:0x1e00
	ds_read_b64_tr_b16 v[220:221], v236 offset:0x2600
	ds_read_b64_tr_b16 v[222:223], v236 offset:0x2e00
	ds_read_b64_tr_b16 v[232:233], v236 offset:0x3600
	ds_read_b64_tr_b16 v[234:235], v236 offset:0x3e00
	s_waitcnt lgkmcnt(8)
	v_mfma_f32_32x32x16_bf16 v[0:15], v[128:131], v[144:147], v[0:15]
	v_mfma_f32_32x32x16_bf16 v[0:15], v[132:135], v[148:151], v[0:15]
	v_mfma_f32_32x32x16_bf16 v[0:15], v[136:139], v[152:155], v[0:15]
	v_mfma_f32_32x32x16_bf16 v[0:15], v[140:143], v[156:159], v[0:15]
	s_waitcnt lgkmcnt(0)
	v_mfma_f32_32x32x16_bf16 v[80:95], v[128:131], v[194:197], v[80:95]
	s_mov_b64 s[24:25], -1
	s_and_b64 vcc, exec, s[50:51]
	v_mfma_f32_32x32x16_bf16 v[80:95], v[132:135], v[214:217], v[80:95]
	v_mfma_f32_32x32x16_bf16 v[80:95], v[136:139], v[220:223], v[80:95]
	v_mfma_f32_32x32x16_bf16 v[80:95], v[140:143], v[232:235], v[80:95]
	s_cbranch_vccz .LBB0_398
	s_waitcnt vmcnt(0) lgkmcnt(0)
	s_barrier
	s_mov_b64 s[24:25], 0
